# GEMM K-loops: first 4 MFMAs of each MFMA phase issued at priority 0 before 's_setprio 1; s_barrier' (fill the matrix pipe while the barrier resolves)
# speedup vs baseline: 1.0005x; 1.0005x over previous
; #define PG8_STAGE(bufoff, gbase, voff) do { _Pragma("unroll") for (int _i = 0; _i < 2; ++_i) \
;         __builtin_amdgcn_global_load_lds((const unsigned*)((const char*)(gbase) + (voff)[_i]), (PG8_LAS unsigned*)(lds + (bufoff) + ldsw + _i * 8192), 16, 0, 0); } while (0)
; #define PG8_LDA(dst, b, h) do { _Pragma("unroll") for (int m = 0; m < 4; ++m) _Pragma("unroll") for (int k = 0; k < 2; ++k) dst[m][k] = *(const PG8_LAS bf16x8*)(lds + PG8_SA(b, h) + aoff + m * 2048 + k * 1024); } while (0)
; #define PG8_LDB(dst, b, h) do { _Pragma("unroll") for (int n = 0; n < 2; ++n) _Pragma("unroll") for (int k = 0; k < 2; ++k) dst[n][k] = *(const PG8_LAS bf16x8*)(lds + PG8_SB(b, h) + boff + n * 2048 + k * 1024); } while (0)
; #define PG8_MMA(ai, bj, At, Bt) do { __builtin_amdgcn_s_setprio(1); _Pragma("unroll") for (int m = 0; m < 4; ++m) _Pragma("unroll") for (int n = 0; n < 2; ++n) _Pragma("unroll") for (int k = 0; k < 2; ++k) \
;         acc[ai][bj][m][n] = __builtin_amdgcn_mfma_f32_16x16x32_bf16(Bt[n][k], At[m][k], acc[ai][bj][m][n], 0, 0, 0); __builtin_amdgcn_s_setprio(0); } while (0)
; #define PG8_WAIT_V(n) asm volatile("s_waitcnt vmcnt(" #n ")" ::: "memory")
; #define PG8_WAIT_L(n) asm volatile("s_waitcnt lgkmcnt(" #n ")" ::: "memory")
; template <class Epi, class Sched, bool ALIGN_EPI = false, bool SP2 = false>
; __device__ __forceinline__ void gemm_phase(PG8_LAS unsigned char* lds, const Gemm g, const Sched& S, const Epi& E, const int tid) {
;     ...
;             const bool last = (t == nt - 2);
;             const char* a1 = cA + (size_t)(t + 1) * kstep;
;             const char* a2 = last ? nA : cA + (size_t)(t + 2) * kstep; const char* b2 = last ? nB : cB + (size_t)(t + 2) * kstep;
;             const char* a3 = a2 + kstep; const char* b3 = b2 + kstep;
;             if (last && has_next) S.a_ready(nxt);
;             if constexpr (SP2) {
;             PG8_LDB(B0, 0, 0); PG8_LDB(B1, 0, 1); PG8_SCHED; PG8_LDA(At, 0, 0); PG8_STAGE(PG8_SA(1, 1), a1 + hstep, voffA);
;             PG8_WAIT_V(8); PG8_WAIT_L(0); PG8_BAR; PG8_MMA(0, 0, At, B0); PG8_MMA(0, 1, At, B1); PG8_BAR; PG8_SCHED;
;             PG8_LDA(At, 0, 1); PG8_STAGE(PG8_SB(0, 0), b2, voffB); PG8_STAGE(PG8_SB(0, 1), b2 + hstep, voffB); PG8_STAGE(PG8_SA(0, 0), a2, voffA);
;             PG8_WAIT_V(8); PG8_WAIT_L(0); PG8_BAR; PG8_MMA(1, 0, At, B0); PG8_MMA(1, 1, At, B1); PG8_BAR; PG8_SCHED;
.LBB0_211:
	s_add_u32 s56, s54, 0xfff80080
	s_addc_u32 s57, s55, -1
	s_add_i32 s78, 0, 0x10000
	s_cmp_eq_u32 s77, 28
	s_cselect_b32 s59, s49, s57
	s_cselect_b32 s58, s72, s56
	s_cselect_b32 s57, s47, s76
	s_cselect_b32 s56, s73, s75
	s_add_i32 s80, 0, 0x14000
	v_add_u32_e32 v154, s78, v160
	v_add_u32_e32 v158, s80, v160
	ds_read_b128 v[142:145], v154
	ds_read_b128 v[146:149], v154 offset:1024
	ds_read_b128 v[150:153], v154 offset:2048
	ds_read_b128 v[154:157], v154 offset:3072
	ds_read_b128 v[164:167], v158
	ds_read_b128 v[168:171], v158 offset:1024
	ds_read_b128 v[172:175], v158 offset:2048
	ds_read_b128 v[176:179], v158 offset:3072
	v_lshl_add_u64 v[158:159], s[54:55], 0, v[140:141]
	s_add_i32 m0, s61, 0xc000
	ds_read_b128 v[186:189], v162
	ds_read_b128 v[190:193], v162 offset:1024
	ds_read_b128 v[194:197], v162 offset:2048
	ds_read_b128 v[198:201], v162 offset:3072
	ds_read_b128 v[202:205], v162 offset:4096
	ds_read_b128 v[206:209], v162 offset:5120
	ds_read_b128 v[210:213], v162 offset:6144
	ds_read_b128 v[214:217], v162 offset:7168
	global_load_lds_dwordx4 v[158:159], off
	v_lshl_add_u64 v[158:159], s[54:55], 0, v[138:139]
	s_add_i32 m0, s61, 0xe000
	s_nop 0
	global_load_lds_dwordx4 v[158:159], off
	s_waitcnt vmcnt(8)
	s_waitcnt lgkmcnt(0)
	v_mfma_f32_16x16x32_bf16 v[130:133], v[142:145], v[186:189], v[130:133]
	v_mfma_f32_16x16x32_bf16 v[126:129], v[150:153], v[186:189], v[126:129]
	v_mfma_f32_16x16x32_bf16 v[114:117], v[142:145], v[194:197], v[114:117]
	v_mfma_f32_16x16x32_bf16 v[106:109], v[150:153], v[194:197], v[106:109]
	s_setprio 1
	s_barrier
	v_mfma_f32_16x16x32_bf16 v[92:95], v[142:145], v[202:205], v[92:95]
	v_mfma_f32_16x16x32_bf16 v[84:87], v[150:153], v[202:205], v[84:87]
	v_mfma_f32_16x16x32_bf16 v[76:79], v[142:145], v[210:213], v[76:79]
	v_mfma_f32_16x16x32_bf16 v[68:71], v[150:153], v[210:213], v[68:71]
	v_mfma_f32_16x16x32_bf16 v[130:133], v[146:149], v[190:193], v[130:133]
	v_mfma_f32_16x16x32_bf16 v[126:129], v[154:157], v[190:193], v[126:129]
	v_mfma_f32_16x16x32_bf16 v[114:117], v[146:149], v[198:201], v[114:117]
	v_mfma_f32_16x16x32_bf16 v[106:109], v[154:157], v[198:201], v[106:109]
	v_mfma_f32_16x16x32_bf16 v[92:95], v[146:149], v[206:209], v[92:95]
	v_mfma_f32_16x16x32_bf16 v[84:87], v[154:157], v[206:209], v[84:87]
	v_mfma_f32_16x16x32_bf16 v[76:79], v[146:149], v[214:217], v[76:79]
	v_mfma_f32_16x16x32_bf16 v[68:71], v[154:157], v[214:217], v[68:71]
	v_mfma_f32_16x16x32_bf16 v[122:125], v[164:167], v[186:189], v[122:125]
	v_mfma_f32_16x16x32_bf16 v[118:121], v[172:175], v[186:189], v[118:121]
	v_mfma_f32_16x16x32_bf16 v[110:113], v[164:167], v[194:197], v[110:113]
	v_mfma_f32_16x16x32_bf16 v[102:105], v[172:175], v[194:197], v[102:105]
	v_mfma_f32_16x16x32_bf16 v[88:91], v[164:167], v[202:205], v[88:91]
	v_mfma_f32_16x16x32_bf16 v[80:83], v[172:175], v[202:205], v[80:83]
	v_mfma_f32_16x16x32_bf16 v[72:75], v[164:167], v[210:213], v[72:75]
	v_mfma_f32_16x16x32_bf16 v[64:67], v[172:175], v[210:213], v[64:67]
	v_mfma_f32_16x16x32_bf16 v[122:125], v[168:171], v[190:193], v[122:125]
	v_mfma_f32_16x16x32_bf16 v[118:121], v[176:179], v[190:193], v[118:121]
	v_mfma_f32_16x16x32_bf16 v[110:113], v[168:171], v[198:201], v[110:113]
	v_mfma_f32_16x16x32_bf16 v[102:105], v[176:179], v[198:201], v[102:105]
	v_mfma_f32_16x16x32_bf16 v[88:91], v[168:171], v[206:209], v[88:91]
	v_mfma_f32_16x16x32_bf16 v[80:83], v[176:179], v[206:209], v[80:83]
	v_mfma_f32_16x16x32_bf16 v[72:75], v[168:171], v[214:217], v[72:75]
	v_mfma_f32_16x16x32_bf16 v[64:67], v[176:179], v[214:217], v[64:67]
	s_barrier
	s_setprio 0
	s_add_i32 s78, s78, s60
	v_lshl_add_u64 v[158:159], s[56:57], 0, v[96:97]
	s_mov_b32 m0, s78
	ds_read_b128 v[186:189], v162 offset:16384
	ds_read_b128 v[190:193], v162 offset:17408
	ds_read_b128 v[194:197], v162 offset:18432
	ds_read_b128 v[198:201], v162 offset:19456
	ds_read_b128 v[202:205], v162 offset:20480
	ds_read_b128 v[206:209], v162 offset:21504
	ds_read_b128 v[210:213], v162 offset:22528
	ds_read_b128 v[214:217], v162 offset:23552
	global_load_lds_dwordx4 v[158:159], off
	s_add_i32 m0, s78, 0x2000
	s_add_u32 s78, s56, 0x80000
	v_lshl_add_u64 v[180:181], s[56:57], 0, v[98:99]
	s_addc_u32 s79, s57, 0
	s_add_i32 s80, s80, s60
	global_load_lds_dwordx4 v[180:181], off
	v_lshl_add_u64 v[218:219], s[78:79], 0, v[96:97]
	s_mov_b32 m0, s80
	v_lshl_add_u64 v[220:221], s[58:59], 0, v[134:135]
	global_load_lds_dwordx4 v[218:219], off
	v_lshl_add_u64 v[218:219], s[78:79], 0, v[98:99]
	s_add_i32 m0, s80, 0x2000
	s_nop 0
	global_load_lds_dwordx4 v[218:219], off
	v_lshl_add_u64 v[218:219], s[58:59], 0, v[136:137]
	s_mov_b32 m0, s61
	s_nop 0
	global_load_lds_dwordx4 v[218:219], off
	s_mov_b32 m0, s64
	s_nop 0
	global_load_lds_dwordx4 v[220:221], off
	s_waitcnt vmcnt(8)
	s_waitcnt lgkmcnt(0)
	v_mfma_f32_16x16x32_bf16 v[60:63], v[142:145], v[186:189], v[60:63]
	v_mfma_f32_16x16x32_bf16 v[52:55], v[150:153], v[186:189], v[52:55]
	v_mfma_f32_16x16x32_bf16 v[44:47], v[142:145], v[194:197], v[44:47]
	v_mfma_f32_16x16x32_bf16 v[36:39], v[150:153], v[194:197], v[36:39]
	s_setprio 1
	s_barrier
; #define PG8_STAGE(bufoff, gbase, voff) do { _Pragma("unroll") for (int _i = 0; _i < 2; ++_i) \
;         __builtin_amdgcn_global_load_lds((const unsigned*)((const char*)(gbase) + (voff)[_i]), (PG8_LAS unsigned*)(lds + (bufoff) + ldsw + _i * 8192), 16, 0, 0); } while (0)
; #define PG8_LDA(dst, b, h) do { _Pragma("unroll") for (int m = 0; m < 4; ++m) _Pragma("unroll") for (int k = 0; k < 2; ++k) dst[m][k] = *(const PG8_LAS bf16x8*)(lds + PG8_SA(b, h) + aoff + m * 2048 + k * 1024); } while (0)
; #define PG8_LDB(dst, b, h) do { _Pragma("unroll") for (int n = 0; n < 2; ++n) _Pragma("unroll") for (int k = 0; k < 2; ++k) dst[n][k] = *(const PG8_LAS bf16x8*)(lds + PG8_SB(b, h) + boff + n * 2048 + k * 1024); } while (0)
; #define PG8_MMA(ai, bj, At, Bt) do { __builtin_amdgcn_s_setprio(1); _Pragma("unroll") for (int m = 0; m < 4; ++m) _Pragma("unroll") for (int n = 0; n < 2; ++n) _Pragma("unroll") for (int k = 0; k < 2; ++k) \
;         acc[ai][bj][m][n] = __builtin_amdgcn_mfma_f32_16x16x32_bf16(Bt[n][k], At[m][k], acc[ai][bj][m][n], 0, 0, 0); __builtin_amdgcn_s_setprio(0); } while (0)
; #define PG8_WAIT_V(n) asm volatile("s_waitcnt vmcnt(" #n ")" ::: "memory")
; #define PG8_WAIT_L(n) asm volatile("s_waitcnt lgkmcnt(" #n ")" ::: "memory")
; #define PG8_BAR __builtin_amdgcn_s_barrier()
; #define PG8_SCHED __builtin_amdgcn_sched_barrier(0)
; template <class Epi, class Sched, bool ALIGN_EPI = false, bool SP2 = false>
; __device__ __forceinline__ void gemm_phase(PG8_LAS unsigned char* lds, const Gemm g, const Sched& S, const Epi& E, const int tid) {
;     ...
;             PG8_WAIT_V(8); PG8_WAIT_L(0); PG8_BAR; PG8_MMA(1, 0, At, B0); PG8_MMA(1, 1, At, B1); PG8_BAR; PG8_SCHED;
;             PG8_LDB(B0, 1, 0); PG8_LDB(B1, 1, 1); PG8_SCHED; PG8_LDA(At, 1, 0); PG8_STAGE(PG8_SA(0, 1), a2 + hstep, voffA);
;             PG8_WAIT_V(8); PG8_WAIT_L(0); PG8_BAR; PG8_MMA(0, 0, At, B0); PG8_MMA(0, 1, At, B1); PG8_BAR; PG8_SCHED;
	v_mfma_f32_16x16x32_bf16 v[28:31], v[142:145], v[202:205], v[28:31]
	v_mfma_f32_16x16x32_bf16 v[20:23], v[150:153], v[202:205], v[20:23]
	v_mfma_f32_16x16x32_bf16 v[12:15], v[142:145], v[210:213], v[12:15]
	v_mfma_f32_16x16x32_bf16 v[4:7], v[150:153], v[210:213], v[4:7]
	v_mfma_f32_16x16x32_bf16 v[60:63], v[146:149], v[190:193], v[60:63]
	v_mfma_f32_16x16x32_bf16 v[52:55], v[154:157], v[190:193], v[52:55]
	v_mfma_f32_16x16x32_bf16 v[44:47], v[146:149], v[198:201], v[44:47]
	v_mfma_f32_16x16x32_bf16 v[36:39], v[154:157], v[198:201], v[36:39]
	v_mfma_f32_16x16x32_bf16 v[28:31], v[146:149], v[206:209], v[28:31]
	v_mfma_f32_16x16x32_bf16 v[20:23], v[154:157], v[206:209], v[20:23]
	v_mfma_f32_16x16x32_bf16 v[12:15], v[146:149], v[214:217], v[12:15]
	v_mfma_f32_16x16x32_bf16 v[4:7], v[154:157], v[214:217], v[4:7]
	v_mfma_f32_16x16x32_bf16 v[56:59], v[164:167], v[186:189], v[56:59]
	v_mfma_f32_16x16x32_bf16 v[48:51], v[172:175], v[186:189], v[48:51]
	v_mfma_f32_16x16x32_bf16 v[40:43], v[164:167], v[194:197], v[40:43]
	v_mfma_f32_16x16x32_bf16 v[32:35], v[172:175], v[194:197], v[32:35]
	v_mfma_f32_16x16x32_bf16 v[24:27], v[164:167], v[202:205], v[24:27]
	v_mfma_f32_16x16x32_bf16 v[16:19], v[172:175], v[202:205], v[16:19]
	v_mfma_f32_16x16x32_bf16 v[8:11], v[164:167], v[210:213], v[8:11]
	v_mfma_f32_16x16x32_bf16 v[0:3], v[172:175], v[210:213], v[0:3]
	v_mfma_f32_16x16x32_bf16 v[56:59], v[168:171], v[190:193], v[56:59]
	v_mfma_f32_16x16x32_bf16 v[48:51], v[176:179], v[190:193], v[48:51]
	v_mfma_f32_16x16x32_bf16 v[40:43], v[168:171], v[198:201], v[40:43]
	v_mfma_f32_16x16x32_bf16 v[32:35], v[176:179], v[198:201], v[32:35]
	v_mfma_f32_16x16x32_bf16 v[24:27], v[168:171], v[206:209], v[24:27]
	v_mfma_f32_16x16x32_bf16 v[16:19], v[176:179], v[206:209], v[16:19]
	v_mfma_f32_16x16x32_bf16 v[8:11], v[168:171], v[214:217], v[8:11]
	v_mfma_f32_16x16x32_bf16 v[0:3], v[176:179], v[214:217], v[0:3]
	s_barrier
	s_setprio 0
	s_add_i32 s78, 0, 0x18000
	s_add_i32 s79, 0, 0x1c000
	v_add_u32_e32 v154, s78, v160
	v_add_u32_e32 v163, s79, v160
	ds_read_b128 v[142:145], v154
	ds_read_b128 v[146:149], v154 offset:1024
	ds_read_b128 v[150:153], v154 offset:2048
	ds_read_b128 v[154:157], v154 offset:3072
	ds_read_b128 v[164:167], v163
	ds_read_b128 v[168:171], v163 offset:1024
	ds_read_b128 v[172:175], v163 offset:2048
	ds_read_b128 v[176:179], v163 offset:3072
	s_add_u32 s58, s58, 0x80000
	s_addc_u32 s59, s59, 0
	s_mov_b32 m0, s65
	v_lshl_add_u64 v[222:223], s[58:59], 0, v[136:137]
	ds_read_b128 v[186:189], v162 offset:32768
	ds_read_b128 v[190:193], v162 offset:33792
	ds_read_b128 v[194:197], v162 offset:34816
	ds_read_b128 v[198:201], v162 offset:35840
	ds_read_b128 v[202:205], v162 offset:36864
	ds_read_b128 v[206:209], v162 offset:37888
	ds_read_b128 v[210:213], v162 offset:38912
	ds_read_b128 v[214:217], v162 offset:39936
	global_load_lds_dwordx4 v[222:223], off
	v_lshl_add_u64 v[222:223], s[58:59], 0, v[134:135]
	s_mov_b32 m0, s66
	s_nop 0
	global_load_lds_dwordx4 v[222:223], off
	s_waitcnt vmcnt(8)
	s_waitcnt lgkmcnt(0)
	v_mfma_f32_16x16x32_bf16 v[130:133], v[142:145], v[186:189], v[130:133]
	v_mfma_f32_16x16x32_bf16 v[126:129], v[150:153], v[186:189], v[126:129]
	v_mfma_f32_16x16x32_bf16 v[114:117], v[142:145], v[194:197], v[114:117]
	v_mfma_f32_16x16x32_bf16 v[106:109], v[150:153], v[194:197], v[106:109]
	s_setprio 1
	s_barrier
	v_mfma_f32_16x16x32_bf16 v[92:95], v[142:145], v[202:205], v[92:95]
	v_mfma_f32_16x16x32_bf16 v[84:87], v[150:153], v[202:205], v[84:87]
	v_mfma_f32_16x16x32_bf16 v[76:79], v[142:145], v[210:213], v[76:79]
	v_mfma_f32_16x16x32_bf16 v[68:71], v[150:153], v[210:213], v[68:71]
	v_mfma_f32_16x16x32_bf16 v[130:133], v[146:149], v[190:193], v[130:133]
	v_mfma_f32_16x16x32_bf16 v[126:129], v[154:157], v[190:193], v[126:129]
	v_mfma_f32_16x16x32_bf16 v[114:117], v[146:149], v[198:201], v[114:117]
	v_mfma_f32_16x16x32_bf16 v[106:109], v[154:157], v[198:201], v[106:109]
	v_mfma_f32_16x16x32_bf16 v[92:95], v[146:149], v[206:209], v[92:95]
	v_mfma_f32_16x16x32_bf16 v[84:87], v[154:157], v[206:209], v[84:87]
	v_mfma_f32_16x16x32_bf16 v[76:79], v[146:149], v[214:217], v[76:79]
	v_mfma_f32_16x16x32_bf16 v[68:71], v[154:157], v[214:217], v[68:71]
	v_mfma_f32_16x16x32_bf16 v[122:125], v[164:167], v[186:189], v[122:125]
	v_mfma_f32_16x16x32_bf16 v[118:121], v[172:175], v[186:189], v[118:121]
	v_mfma_f32_16x16x32_bf16 v[110:113], v[164:167], v[194:197], v[110:113]
	v_mfma_f32_16x16x32_bf16 v[102:105], v[172:175], v[194:197], v[102:105]
	v_mfma_f32_16x16x32_bf16 v[88:91], v[164:167], v[202:205], v[88:91]
	v_mfma_f32_16x16x32_bf16 v[80:83], v[172:175], v[202:205], v[80:83]
	v_mfma_f32_16x16x32_bf16 v[72:75], v[164:167], v[210:213], v[72:75]
	v_mfma_f32_16x16x32_bf16 v[64:67], v[172:175], v[210:213], v[64:67]
	v_mfma_f32_16x16x32_bf16 v[122:125], v[168:171], v[190:193], v[122:125]
	v_mfma_f32_16x16x32_bf16 v[118:121], v[176:179], v[190:193], v[118:121]
	v_mfma_f32_16x16x32_bf16 v[110:113], v[168:171], v[198:201], v[110:113]
	v_mfma_f32_16x16x32_bf16 v[102:105], v[176:179], v[198:201], v[102:105]
	v_mfma_f32_16x16x32_bf16 v[88:91], v[168:171], v[206:209], v[88:91]
	v_mfma_f32_16x16x32_bf16 v[80:83], v[176:179], v[206:209], v[80:83]
	v_mfma_f32_16x16x32_bf16 v[72:75], v[168:171], v[214:217], v[72:75]
	v_mfma_f32_16x16x32_bf16 v[64:67], v[176:179], v[214:217], v[64:67]
	s_barrier
; #define PG8_STAGE(bufoff, gbase, voff) do { _Pragma("unroll") for (int _i = 0; _i < 2; ++_i) \
;         __builtin_amdgcn_global_load_lds((const unsigned*)((const char*)(gbase) + (voff)[_i]), (PG8_LAS unsigned*)(lds + (bufoff) + ldsw + _i * 8192), 16, 0, 0); } while (0)
; #define PG8_LDA(dst, b, h) do { _Pragma("unroll") for (int m = 0; m < 4; ++m) _Pragma("unroll") for (int k = 0; k < 2; ++k) dst[m][k] = *(const PG8_LAS bf16x8*)(lds + PG8_SA(b, h) + aoff + m * 2048 + k * 1024); } while (0)
; #define PG8_MMA(ai, bj, At, Bt) do { __builtin_amdgcn_s_setprio(1); _Pragma("unroll") for (int m = 0; m < 4; ++m) _Pragma("unroll") for (int n = 0; n < 2; ++n) _Pragma("unroll") for (int k = 0; k < 2; ++k) \
;         acc[ai][bj][m][n] = __builtin_amdgcn_mfma_f32_16x16x32_bf16(Bt[n][k], At[m][k], acc[ai][bj][m][n], 0, 0, 0); __builtin_amdgcn_s_setprio(0); } while (0)
; #define PG8_WAIT_V(n) asm volatile("s_waitcnt vmcnt(" #n ")" ::: "memory")
; #define PG8_WAIT_L(n) asm volatile("s_waitcnt lgkmcnt(" #n ")" ::: "memory")
; #define PG8_BAR __builtin_amdgcn_s_barrier()
; #define PG8_SCHED __builtin_amdgcn_sched_barrier(0)
; template <class Epi, class Sched, bool ALIGN_EPI = false, bool SP2 = false>
; __device__ __forceinline__ void gemm_phase(PG8_LAS unsigned char* lds, const Gemm g, const Sched& S, const Epi& E, const int tid) {
;     ...
;             PG8_LDA(At, 1, 1); PG8_STAGE(PG8_SB(1, 0), b3, voffB); PG8_STAGE(PG8_SB(1, 1), b3 + hstep, voffB); PG8_STAGE(PG8_SA(1, 0), a3, voffA);
;             PG8_WAIT_V(8); PG8_WAIT_L(0); PG8_BAR; PG8_MMA(1, 0, At, B0); PG8_MMA(1, 1, At, B1); PG8_BAR; PG8_SCHED;
;     ...
;         if constexpr (ALIGN_EPI) { if (wr == 0) PG8_BAR; }
	s_setprio 0
	s_add_i32 s58, s78, s60
	v_lshl_add_u64 v[158:159], v[158:159], 0, s[28:29]
	s_mov_b32 m0, s58
	ds_read_b128 v[186:189], v162 offset:49152
	ds_read_b128 v[190:193], v162 offset:50176
	ds_read_b128 v[194:197], v162 offset:51200
	ds_read_b128 v[198:201], v162 offset:52224
	ds_read_b128 v[202:205], v162 offset:53248
	ds_read_b128 v[206:209], v162 offset:54272
	ds_read_b128 v[210:213], v162 offset:55296
	ds_read_b128 v[214:217], v162 offset:56320
	global_load_lds_dwordx4 v[158:159], off
	s_add_i32 m0, s58, 0x2000
	s_add_u32 s56, s56, 0x80080
	v_lshl_add_u64 v[158:159], v[180:181], 0, s[28:29]
	s_addc_u32 s57, s57, 0
	s_add_i32 s58, s79, s60
	global_load_lds_dwordx4 v[158:159], off
	v_lshl_add_u64 v[158:159], s[56:57], 0, v[96:97]
	s_mov_b32 m0, s58
	s_nop 0
	global_load_lds_dwordx4 v[158:159], off
	v_lshl_add_u64 v[158:159], s[56:57], 0, v[98:99]
	s_add_i32 m0, s58, 0x2000
	s_nop 0
	global_load_lds_dwordx4 v[158:159], off
	v_lshl_add_u64 v[158:159], v[218:219], 0, s[28:29]
	s_mov_b32 m0, s67
	s_nop 0
	global_load_lds_dwordx4 v[158:159], off
	v_lshl_add_u64 v[158:159], v[220:221], 0, s[28:29]
	s_mov_b32 m0, s68
	s_nop 0
	global_load_lds_dwordx4 v[158:159], off
	s_waitcnt vmcnt(8)
	s_waitcnt lgkmcnt(0)
	v_mfma_f32_16x16x32_bf16 v[60:63], v[142:145], v[186:189], v[60:63]
	v_mfma_f32_16x16x32_bf16 v[52:55], v[150:153], v[186:189], v[52:55]
	v_mfma_f32_16x16x32_bf16 v[44:47], v[142:145], v[194:197], v[44:47]
	v_mfma_f32_16x16x32_bf16 v[36:39], v[150:153], v[194:197], v[36:39]
	s_setprio 1
	s_barrier
	v_mfma_f32_16x16x32_bf16 v[28:31], v[142:145], v[202:205], v[28:31]
	v_mfma_f32_16x16x32_bf16 v[20:23], v[150:153], v[202:205], v[20:23]
	v_mfma_f32_16x16x32_bf16 v[12:15], v[142:145], v[210:213], v[12:15]
	v_mfma_f32_16x16x32_bf16 v[4:7], v[150:153], v[210:213], v[4:7]
	v_mfma_f32_16x16x32_bf16 v[60:63], v[146:149], v[190:193], v[60:63]
	v_mfma_f32_16x16x32_bf16 v[52:55], v[154:157], v[190:193], v[52:55]
	v_mfma_f32_16x16x32_bf16 v[44:47], v[146:149], v[198:201], v[44:47]
	v_mfma_f32_16x16x32_bf16 v[36:39], v[154:157], v[198:201], v[36:39]
	v_mfma_f32_16x16x32_bf16 v[28:31], v[146:149], v[206:209], v[28:31]
	v_mfma_f32_16x16x32_bf16 v[20:23], v[154:157], v[206:209], v[20:23]
	v_mfma_f32_16x16x32_bf16 v[12:15], v[146:149], v[214:217], v[12:15]
	v_mfma_f32_16x16x32_bf16 v[4:7], v[154:157], v[214:217], v[4:7]
	v_mfma_f32_16x16x32_bf16 v[56:59], v[164:167], v[186:189], v[56:59]
	v_mfma_f32_16x16x32_bf16 v[48:51], v[172:175], v[186:189], v[48:51]
	v_mfma_f32_16x16x32_bf16 v[40:43], v[164:167], v[194:197], v[40:43]
	v_mfma_f32_16x16x32_bf16 v[32:35], v[172:175], v[194:197], v[32:35]
	v_mfma_f32_16x16x32_bf16 v[24:27], v[164:167], v[202:205], v[24:27]
	v_mfma_f32_16x16x32_bf16 v[16:19], v[172:175], v[202:205], v[16:19]
	v_mfma_f32_16x16x32_bf16 v[8:11], v[164:167], v[210:213], v[8:11]
	v_mfma_f32_16x16x32_bf16 v[0:3], v[172:175], v[210:213], v[0:3]
	v_mfma_f32_16x16x32_bf16 v[56:59], v[168:171], v[190:193], v[56:59]
	v_mfma_f32_16x16x32_bf16 v[48:51], v[176:179], v[190:193], v[48:51]
	v_mfma_f32_16x16x32_bf16 v[40:43], v[168:171], v[198:201], v[40:43]
	v_mfma_f32_16x16x32_bf16 v[32:35], v[176:179], v[198:201], v[32:35]
	v_mfma_f32_16x16x32_bf16 v[24:27], v[168:171], v[206:209], v[24:27]
	v_mfma_f32_16x16x32_bf16 v[16:19], v[176:179], v[206:209], v[16:19]
	v_mfma_f32_16x16x32_bf16 v[8:11], v[168:171], v[214:217], v[8:11]
	v_mfma_f32_16x16x32_bf16 v[0:3], v[176:179], v[214:217], v[0:3]
	s_barrier
	s_setprio 0
	s_add_i32 s77, s77, 2
	s_add_u32 s75, s75, 0x100
	s_addc_u32 s76, s76, 0
	s_add_u32 s54, s54, 0x100
	s_addc_u32 s55, s55, 0
	s_cmp_gt_u32 s77, 29
	s_cbranch_scc0 .LBB0_211
	s_and_b64 vcc, exec, s[44:45]
	s_cbranch_vccz .LBB0_214
	s_barrier

; #define PG8_STAGE(bufoff, gbase, voff) do { _Pragma("unroll") for (int _i = 0; _i < 2; ++_i) \
;         __builtin_amdgcn_global_load_lds((const unsigned*)((const char*)(gbase) + (voff)[_i]), (PG8_LAS unsigned*)(lds + (bufoff) + ldsw + _i * 8192), 16, 0, 0); } while (0)
; #define PG8_LDA(dst, b, h) do { _Pragma("unroll") for (int m = 0; m < 4; ++m) _Pragma("unroll") for (int k = 0; k < 2; ++k) dst[m][k] = *(const PG8_LAS bf16x8*)(lds + PG8_SA(b, h) + aoff + m * 2048 + k * 1024); } while (0)
; #define PG8_LDB(dst, b, h) do { _Pragma("unroll") for (int n = 0; n < 2; ++n) _Pragma("unroll") for (int k = 0; k < 2; ++k) dst[n][k] = *(const PG8_LAS bf16x8*)(lds + PG8_SB(b, h) + boff + n * 2048 + k * 1024); } while (0)
; #define PG8_MMA(ai, bj, At, Bt) do { __builtin_amdgcn_s_setprio(1); _Pragma("unroll") for (int m = 0; m < 4; ++m) _Pragma("unroll") for (int n = 0; n < 2; ++n) _Pragma("unroll") for (int k = 0; k < 2; ++k) \
;         acc[ai][bj][m][n] = __builtin_amdgcn_mfma_f32_16x16x32_bf16(Bt[n][k], At[m][k], acc[ai][bj][m][n], 0, 0, 0); __builtin_amdgcn_s_setprio(0); } while (0)
; #define PG8_WAIT_V(n) asm volatile("s_waitcnt vmcnt(" #n ")" ::: "memory")
; #define PG8_WAIT_L(n) asm volatile("s_waitcnt lgkmcnt(" #n ")" ::: "memory")
; template <class Epi, class Sched, bool ALIGN_EPI = false, bool SP2 = false>
; __device__ __forceinline__ void gemm_phase(PG8_LAS unsigned char* lds, const Gemm g, const Sched& S, const Epi& E, const int tid) {
;     ...
;             const bool last = (t == nt - 2);
;             const char* a1 = cA + (size_t)(t + 1) * kstep;
;             const char* a2 = last ? nA : cA + (size_t)(t + 2) * kstep; const char* b2 = last ? nB : cB + (size_t)(t + 2) * kstep;
;             const char* a3 = a2 + kstep; const char* b3 = b2 + kstep;
;             if (last && has_next) S.a_ready(nxt);
;             if constexpr (SP2) {
;             PG8_LDB(B0, 0, 0); PG8_LDB(B1, 0, 1); PG8_SCHED; PG8_LDA(At, 0, 0); PG8_STAGE(PG8_SA(1, 1), a1 + hstep, voffA);
;             PG8_WAIT_V(8); PG8_WAIT_L(0); PG8_BAR; PG8_MMA(0, 0, At, B0); PG8_MMA(0, 1, At, B1); PG8_BAR; PG8_SCHED;
;             PG8_LDA(At, 0, 1); PG8_STAGE(PG8_SB(0, 0), b2, voffB); PG8_STAGE(PG8_SB(0, 1), b2 + hstep, voffB); PG8_STAGE(PG8_SA(0, 0), a2, voffA);
;             PG8_WAIT_V(8); PG8_WAIT_L(0); PG8_BAR; PG8_MMA(1, 0, At, B0); PG8_MMA(1, 1, At, B1); PG8_BAR; PG8_SCHED;
.LBB0_403:
	s_add_u32 s52, s50, 0x100
	s_addc_u32 s53, s51, 0
	s_add_i32 s76, 0, 0x10000
	s_cmpk_eq_i32 s75, 0x54
	s_cselect_b32 s57, s45, s53
	s_cselect_b32 s56, s44, s52
	s_cselect_b32 s55, s47, s73
	s_cselect_b32 s54, s46, s72
	s_add_i32 s77, 0, 0x14000
	v_add_u32_e32 v146, s76, v233
	v_add_u32_e32 v162, s77, v233
	ds_read_b128 v[126:129], v146
	ds_read_b128 v[130:133], v146 offset:1024
	ds_read_b128 v[142:145], v146 offset:2048
	ds_read_b128 v[146:149], v146 offset:3072
	ds_read_b128 v[150:153], v162
	ds_read_b128 v[154:157], v162 offset:1024
	ds_read_b128 v[158:161], v162 offset:2048
	ds_read_b128 v[162:165], v162 offset:3072
	v_lshl_add_u64 v[210:211], s[50:51], 0, v[192:193]
	s_add_i32 m0, s60, 0xc000
	ds_read_b128 v[166:169], v236
	ds_read_b128 v[170:173], v236 offset:1024
	ds_read_b128 v[174:177], v236 offset:2048
	ds_read_b128 v[178:181], v236 offset:3072
	ds_read_b128 v[194:197], v236 offset:4096
	ds_read_b128 v[198:201], v236 offset:5120
	ds_read_b128 v[202:205], v236 offset:6144
	ds_read_b128 v[206:209], v236 offset:7168
	global_load_lds_dwordx4 v[210:211], off
	v_lshl_add_u64 v[210:211], s[50:51], 0, v[190:191]
	s_add_i32 m0, s60, 0xe000
	s_nop 0
	global_load_lds_dwordx4 v[210:211], off
	s_waitcnt vmcnt(8)
	s_waitcnt lgkmcnt(0)
	v_mfma_f32_16x16x32_bf16 v[138:141], v[126:129], v[166:169], v[138:141]
	v_mfma_f32_16x16x32_bf16 v[134:137], v[142:145], v[166:169], v[134:137]
	v_mfma_f32_16x16x32_bf16 v[114:117], v[126:129], v[174:177], v[114:117]
	v_mfma_f32_16x16x32_bf16 v[110:113], v[142:145], v[174:177], v[110:113]
	s_setprio 1
	s_barrier
	v_mfma_f32_16x16x32_bf16 v[92:95], v[126:129], v[194:197], v[92:95]
	v_mfma_f32_16x16x32_bf16 v[88:91], v[142:145], v[194:197], v[88:91]
	v_mfma_f32_16x16x32_bf16 v[76:79], v[126:129], v[202:205], v[76:79]
	v_mfma_f32_16x16x32_bf16 v[72:75], v[142:145], v[202:205], v[72:75]
	v_mfma_f32_16x16x32_bf16 v[138:141], v[130:133], v[170:173], v[138:141]
	v_mfma_f32_16x16x32_bf16 v[134:137], v[146:149], v[170:173], v[134:137]
	v_mfma_f32_16x16x32_bf16 v[114:117], v[130:133], v[178:181], v[114:117]
	v_mfma_f32_16x16x32_bf16 v[110:113], v[146:149], v[178:181], v[110:113]
	v_mfma_f32_16x16x32_bf16 v[92:95], v[130:133], v[198:201], v[92:95]
	v_mfma_f32_16x16x32_bf16 v[88:91], v[146:149], v[198:201], v[88:91]
	v_mfma_f32_16x16x32_bf16 v[76:79], v[130:133], v[206:209], v[76:79]
	v_mfma_f32_16x16x32_bf16 v[72:75], v[146:149], v[206:209], v[72:75]
	v_mfma_f32_16x16x32_bf16 v[122:125], v[150:153], v[166:169], v[122:125]
	v_mfma_f32_16x16x32_bf16 v[118:121], v[158:161], v[166:169], v[118:121]
	v_mfma_f32_16x16x32_bf16 v[106:109], v[150:153], v[174:177], v[106:109]
	v_mfma_f32_16x16x32_bf16 v[102:105], v[158:161], v[174:177], v[102:105]
	v_mfma_f32_16x16x32_bf16 v[84:87], v[150:153], v[194:197], v[84:87]
	v_mfma_f32_16x16x32_bf16 v[80:83], v[158:161], v[194:197], v[80:83]
	v_mfma_f32_16x16x32_bf16 v[68:71], v[150:153], v[202:205], v[68:71]
	v_mfma_f32_16x16x32_bf16 v[64:67], v[158:161], v[202:205], v[64:67]
	v_mfma_f32_16x16x32_bf16 v[122:125], v[154:157], v[170:173], v[122:125]
	v_mfma_f32_16x16x32_bf16 v[118:121], v[162:165], v[170:173], v[118:121]
	v_mfma_f32_16x16x32_bf16 v[106:109], v[154:157], v[178:181], v[106:109]
	v_mfma_f32_16x16x32_bf16 v[102:105], v[162:165], v[178:181], v[102:105]
	v_mfma_f32_16x16x32_bf16 v[84:87], v[154:157], v[198:201], v[84:87]
	v_mfma_f32_16x16x32_bf16 v[80:83], v[162:165], v[198:201], v[80:83]
	v_mfma_f32_16x16x32_bf16 v[68:71], v[154:157], v[206:209], v[68:71]
	v_mfma_f32_16x16x32_bf16 v[64:67], v[162:165], v[206:209], v[64:67]
	s_barrier
	s_setprio 0
	s_add_i32 s50, s76, s59
	v_lshl_add_u64 v[210:211], s[54:55], 0, v[96:97]
	s_mov_b32 m0, s50
	ds_read_b128 v[166:169], v236 offset:16384
	ds_read_b128 v[170:173], v236 offset:17408
	ds_read_b128 v[174:177], v236 offset:18432
	ds_read_b128 v[178:181], v236 offset:19456
	ds_read_b128 v[194:197], v236 offset:20480
	ds_read_b128 v[198:201], v236 offset:21504
	ds_read_b128 v[202:205], v236 offset:22528
	ds_read_b128 v[206:209], v236 offset:23552
	global_load_lds_dwordx4 v[210:211], off
	s_add_i32 m0, s50, 0x2000
	s_add_u32 s50, s54, 0x160000
	v_lshl_add_u64 v[212:213], s[54:55], 0, v[98:99]
	s_addc_u32 s51, s55, 0
	s_add_i32 s76, s77, s59
	global_load_lds_dwordx4 v[212:213], off
	v_lshl_add_u64 v[214:215], s[50:51], 0, v[96:97]
	s_mov_b32 m0, s76
	v_lshl_add_u64 v[216:217], s[56:57], 0, v[186:187]
	global_load_lds_dwordx4 v[214:215], off
	v_lshl_add_u64 v[214:215], s[50:51], 0, v[98:99]
	s_add_i32 m0, s76, 0x2000
	s_nop 0
	global_load_lds_dwordx4 v[214:215], off
	v_lshl_add_u64 v[214:215], s[56:57], 0, v[188:189]
	s_mov_b32 m0, s60
	s_nop 0
	global_load_lds_dwordx4 v[214:215], off
	s_mov_b32 m0, s61
	s_nop 0
	global_load_lds_dwordx4 v[216:217], off
	s_waitcnt vmcnt(8)
	s_waitcnt lgkmcnt(0)
	v_mfma_f32_16x16x32_bf16 v[60:63], v[126:129], v[166:169], v[60:63]
	v_mfma_f32_16x16x32_bf16 v[56:59], v[142:145], v[166:169], v[56:59]
	v_mfma_f32_16x16x32_bf16 v[44:47], v[126:129], v[174:177], v[44:47]
	v_mfma_f32_16x16x32_bf16 v[40:43], v[142:145], v[174:177], v[40:43]
	s_setprio 1
	s_barrier
; #define PG8_STAGE(bufoff, gbase, voff) do { _Pragma("unroll") for (int _i = 0; _i < 2; ++_i) \
;         __builtin_amdgcn_global_load_lds((const unsigned*)((const char*)(gbase) + (voff)[_i]), (PG8_LAS unsigned*)(lds + (bufoff) + ldsw + _i * 8192), 16, 0, 0); } while (0)
; #define PG8_LDA(dst, b, h) do { _Pragma("unroll") for (int m = 0; m < 4; ++m) _Pragma("unroll") for (int k = 0; k < 2; ++k) dst[m][k] = *(const PG8_LAS bf16x8*)(lds + PG8_SA(b, h) + aoff + m * 2048 + k * 1024); } while (0)
; #define PG8_LDB(dst, b, h) do { _Pragma("unroll") for (int n = 0; n < 2; ++n) _Pragma("unroll") for (int k = 0; k < 2; ++k) dst[n][k] = *(const PG8_LAS bf16x8*)(lds + PG8_SB(b, h) + boff + n * 2048 + k * 1024); } while (0)
; #define PG8_MMA(ai, bj, At, Bt) do { __builtin_amdgcn_s_setprio(1); _Pragma("unroll") for (int m = 0; m < 4; ++m) _Pragma("unroll") for (int n = 0; n < 2; ++n) _Pragma("unroll") for (int k = 0; k < 2; ++k) \
;         acc[ai][bj][m][n] = __builtin_amdgcn_mfma_f32_16x16x32_bf16(Bt[n][k], At[m][k], acc[ai][bj][m][n], 0, 0, 0); __builtin_amdgcn_s_setprio(0); } while (0)
; #define PG8_WAIT_V(n) asm volatile("s_waitcnt vmcnt(" #n ")" ::: "memory")
; #define PG8_WAIT_L(n) asm volatile("s_waitcnt lgkmcnt(" #n ")" ::: "memory")
; #define PG8_BAR __builtin_amdgcn_s_barrier()
; #define PG8_SCHED __builtin_amdgcn_sched_barrier(0)
; template <class Epi, class Sched, bool ALIGN_EPI = false, bool SP2 = false>
; __device__ __forceinline__ void gemm_phase(PG8_LAS unsigned char* lds, const Gemm g, const Sched& S, const Epi& E, const int tid) {
;     ...
;             PG8_WAIT_V(8); PG8_WAIT_L(0); PG8_BAR; PG8_MMA(1, 0, At, B0); PG8_MMA(1, 1, At, B1); PG8_BAR; PG8_SCHED;
;             PG8_LDB(B0, 1, 0); PG8_LDB(B1, 1, 1); PG8_SCHED; PG8_LDA(At, 1, 0); PG8_STAGE(PG8_SA(0, 1), a2 + hstep, voffA);
;             PG8_WAIT_V(8); PG8_WAIT_L(0); PG8_BAR; PG8_MMA(0, 0, At, B0); PG8_MMA(0, 1, At, B1); PG8_BAR; PG8_SCHED;
	v_mfma_f32_16x16x32_bf16 v[28:31], v[126:129], v[194:197], v[28:31]
	v_mfma_f32_16x16x32_bf16 v[24:27], v[142:145], v[194:197], v[24:27]
	v_mfma_f32_16x16x32_bf16 v[12:15], v[126:129], v[202:205], v[12:15]
	v_mfma_f32_16x16x32_bf16 v[8:11], v[142:145], v[202:205], v[8:11]
	v_mfma_f32_16x16x32_bf16 v[60:63], v[130:133], v[170:173], v[60:63]
	v_mfma_f32_16x16x32_bf16 v[56:59], v[146:149], v[170:173], v[56:59]
	v_mfma_f32_16x16x32_bf16 v[44:47], v[130:133], v[178:181], v[44:47]
	v_mfma_f32_16x16x32_bf16 v[40:43], v[146:149], v[178:181], v[40:43]
	v_mfma_f32_16x16x32_bf16 v[28:31], v[130:133], v[198:201], v[28:31]
	v_mfma_f32_16x16x32_bf16 v[24:27], v[146:149], v[198:201], v[24:27]
	v_mfma_f32_16x16x32_bf16 v[12:15], v[130:133], v[206:209], v[12:15]
	v_mfma_f32_16x16x32_bf16 v[8:11], v[146:149], v[206:209], v[8:11]
	v_mfma_f32_16x16x32_bf16 v[52:55], v[150:153], v[166:169], v[52:55]
	v_mfma_f32_16x16x32_bf16 v[48:51], v[158:161], v[166:169], v[48:51]
	v_mfma_f32_16x16x32_bf16 v[36:39], v[150:153], v[174:177], v[36:39]
	v_mfma_f32_16x16x32_bf16 v[32:35], v[158:161], v[174:177], v[32:35]
	v_mfma_f32_16x16x32_bf16 v[20:23], v[150:153], v[194:197], v[20:23]
	v_mfma_f32_16x16x32_bf16 v[16:19], v[158:161], v[194:197], v[16:19]
	v_mfma_f32_16x16x32_bf16 v[4:7], v[150:153], v[202:205], v[4:7]
	v_mfma_f32_16x16x32_bf16 v[0:3], v[158:161], v[202:205], v[0:3]
	v_mfma_f32_16x16x32_bf16 v[52:55], v[154:157], v[170:173], v[52:55]
	v_mfma_f32_16x16x32_bf16 v[48:51], v[162:165], v[170:173], v[48:51]
	v_mfma_f32_16x16x32_bf16 v[36:39], v[154:157], v[178:181], v[36:39]
	v_mfma_f32_16x16x32_bf16 v[32:35], v[162:165], v[178:181], v[32:35]
	v_mfma_f32_16x16x32_bf16 v[20:23], v[154:157], v[198:201], v[20:23]
	v_mfma_f32_16x16x32_bf16 v[16:19], v[162:165], v[198:201], v[16:19]
	v_mfma_f32_16x16x32_bf16 v[4:7], v[154:157], v[206:209], v[4:7]
	v_mfma_f32_16x16x32_bf16 v[0:3], v[162:165], v[206:209], v[0:3]
	s_barrier
	s_setprio 0
	s_add_i32 s76, 0, 0x18000
	s_add_i32 s77, 0, 0x1c000
	v_add_u32_e32 v146, s76, v233
	v_add_u32_e32 v162, s77, v233
	ds_read_b128 v[126:129], v146
	ds_read_b128 v[130:133], v146 offset:1024
	ds_read_b128 v[142:145], v146 offset:2048
	ds_read_b128 v[146:149], v146 offset:3072
	ds_read_b128 v[150:153], v162
	ds_read_b128 v[154:157], v162 offset:1024
	ds_read_b128 v[158:161], v162 offset:2048
	ds_read_b128 v[162:165], v162 offset:3072
	s_add_u32 s50, s56, 0x160000
	s_addc_u32 s51, s57, 0
	s_mov_b32 m0, s64
	v_lshl_add_u64 v[218:219], s[50:51], 0, v[188:189]
	ds_read_b128 v[166:169], v236 offset:32768
	ds_read_b128 v[170:173], v236 offset:33792
	ds_read_b128 v[174:177], v236 offset:34816
	ds_read_b128 v[178:181], v236 offset:35840
	ds_read_b128 v[194:197], v236 offset:36864
	ds_read_b128 v[198:201], v236 offset:37888
	ds_read_b128 v[202:205], v236 offset:38912
	ds_read_b128 v[206:209], v236 offset:39936
	global_load_lds_dwordx4 v[218:219], off
	v_lshl_add_u64 v[218:219], s[50:51], 0, v[186:187]
	s_mov_b32 m0, s65
	s_nop 0
	global_load_lds_dwordx4 v[218:219], off
	s_waitcnt vmcnt(8)
	s_waitcnt lgkmcnt(0)
	v_mfma_f32_16x16x32_bf16 v[138:141], v[126:129], v[166:169], v[138:141]
	v_mfma_f32_16x16x32_bf16 v[134:137], v[142:145], v[166:169], v[134:137]
	v_mfma_f32_16x16x32_bf16 v[114:117], v[126:129], v[174:177], v[114:117]
	v_mfma_f32_16x16x32_bf16 v[110:113], v[142:145], v[174:177], v[110:113]
	s_setprio 1
	s_barrier
	v_mfma_f32_16x16x32_bf16 v[92:95], v[126:129], v[194:197], v[92:95]
	v_mfma_f32_16x16x32_bf16 v[88:91], v[142:145], v[194:197], v[88:91]
	v_mfma_f32_16x16x32_bf16 v[76:79], v[126:129], v[202:205], v[76:79]
	v_mfma_f32_16x16x32_bf16 v[72:75], v[142:145], v[202:205], v[72:75]
	v_mfma_f32_16x16x32_bf16 v[138:141], v[130:133], v[170:173], v[138:141]
	v_mfma_f32_16x16x32_bf16 v[134:137], v[146:149], v[170:173], v[134:137]
	v_mfma_f32_16x16x32_bf16 v[114:117], v[130:133], v[178:181], v[114:117]
	v_mfma_f32_16x16x32_bf16 v[110:113], v[146:149], v[178:181], v[110:113]
	v_mfma_f32_16x16x32_bf16 v[92:95], v[130:133], v[198:201], v[92:95]
	v_mfma_f32_16x16x32_bf16 v[88:91], v[146:149], v[198:201], v[88:91]
	v_mfma_f32_16x16x32_bf16 v[76:79], v[130:133], v[206:209], v[76:79]
	v_mfma_f32_16x16x32_bf16 v[72:75], v[146:149], v[206:209], v[72:75]
	v_mfma_f32_16x16x32_bf16 v[122:125], v[150:153], v[166:169], v[122:125]
	v_mfma_f32_16x16x32_bf16 v[118:121], v[158:161], v[166:169], v[118:121]
	v_mfma_f32_16x16x32_bf16 v[106:109], v[150:153], v[174:177], v[106:109]
	v_mfma_f32_16x16x32_bf16 v[102:105], v[158:161], v[174:177], v[102:105]
	v_mfma_f32_16x16x32_bf16 v[84:87], v[150:153], v[194:197], v[84:87]
	v_mfma_f32_16x16x32_bf16 v[80:83], v[158:161], v[194:197], v[80:83]
	v_mfma_f32_16x16x32_bf16 v[68:71], v[150:153], v[202:205], v[68:71]
	v_mfma_f32_16x16x32_bf16 v[64:67], v[158:161], v[202:205], v[64:67]
	v_mfma_f32_16x16x32_bf16 v[122:125], v[154:157], v[170:173], v[122:125]
	v_mfma_f32_16x16x32_bf16 v[118:121], v[162:165], v[170:173], v[118:121]
	v_mfma_f32_16x16x32_bf16 v[106:109], v[154:157], v[178:181], v[106:109]
	v_mfma_f32_16x16x32_bf16 v[102:105], v[162:165], v[178:181], v[102:105]
	v_mfma_f32_16x16x32_bf16 v[84:87], v[154:157], v[198:201], v[84:87]
	v_mfma_f32_16x16x32_bf16 v[80:83], v[162:165], v[198:201], v[80:83]
	v_mfma_f32_16x16x32_bf16 v[68:71], v[154:157], v[206:209], v[68:71]
	v_mfma_f32_16x16x32_bf16 v[64:67], v[162:165], v[206:209], v[64:67]
	s_barrier
; #define PG8_GAS __attribute__((address_space(1)))
; #define PG8_STAGE(bufoff, gbase, voff) do { _Pragma("unroll") for (int _i = 0; _i < 2; ++_i) \
;         __builtin_amdgcn_global_load_lds((const unsigned*)((const char*)(gbase) + (voff)[_i]), (PG8_LAS unsigned*)(lds + (bufoff) + ldsw + _i * 8192), 16, 0, 0); } while (0)
; #define PG8_LDA(dst, b, h) do { _Pragma("unroll") for (int m = 0; m < 4; ++m) _Pragma("unroll") for (int k = 0; k < 2; ++k) dst[m][k] = *(const PG8_LAS bf16x8*)(lds + PG8_SA(b, h) + aoff + m * 2048 + k * 1024); } while (0)
; #define PG8_MMA(ai, bj, At, Bt) do { __builtin_amdgcn_s_setprio(1); _Pragma("unroll") for (int m = 0; m < 4; ++m) _Pragma("unroll") for (int n = 0; n < 2; ++n) _Pragma("unroll") for (int k = 0; k < 2; ++k) \
;         acc[ai][bj][m][n] = __builtin_amdgcn_mfma_f32_16x16x32_bf16(Bt[n][k], At[m][k], acc[ai][bj][m][n], 0, 0, 0); __builtin_amdgcn_s_setprio(0); } while (0)
; #define PG8_WAIT_V(n) asm volatile("s_waitcnt vmcnt(" #n ")" ::: "memory")
; #define PG8_WAIT_L(n) asm volatile("s_waitcnt lgkmcnt(" #n ")" ::: "memory")
; #define PG8_BAR __builtin_amdgcn_s_barrier()
;     __device__ __forceinline__ void operator()(const f32x4 (&acc)[2][2][4][2], const Unit& u, int wr, int wc, int fr, int fq) const {
;         const int row0 = u.pm * BM + wr * 64 + fr, col0 = u.pn * BM + wc * 32 + 8 * fq, lcol = u.pn * BM + (wc * 4 + fq) * 16;
; #pragma unroll
;         for (int ai = 0; ai < 2; ++ai) {
;             u32x4 L4[4], H4[4][2];
; #pragma unroll
;             for (int m = 0; m < 4; ++m) {
;                 const int row = row0 + ai * HALF + m * 16; const size_t off = (size_t)row * 2048 + col0, loff = (size_t)row * 2048 + lcol;
;                 L4[m] = *(const PG8_GAS u32x4*)(lin + loff); H4[m][0] = *(const PG8_GAS u32x4*)(hin + off); H4[m][1] = *(const PG8_GAS u32x4*)(hin + off + HALF);
;             }
; template <class Epi, class Sched, bool ALIGN_EPI = false, bool SP2 = false>
; __device__ __forceinline__ void gemm_phase(PG8_LAS unsigned char* lds, const Gemm g, const Sched& S, const Epi& E, const int tid) {
;     ...
;             PG8_LDA(At, 1, 1); PG8_STAGE(PG8_SB(1, 0), b3, voffB); PG8_STAGE(PG8_SB(1, 1), b3 + hstep, voffB); PG8_STAGE(PG8_SA(1, 0), a3, voffA);
;             PG8_WAIT_V(8); PG8_WAIT_L(0); PG8_BAR; PG8_MMA(1, 0, At, B0); PG8_MMA(1, 1, At, B1); PG8_BAR; PG8_SCHED;
	s_setprio 0
	s_add_i32 s50, s76, s59
	v_lshl_add_u64 v[210:211], v[210:211], 0, s[28:29]
	s_mov_b32 m0, s50
	ds_read_b128 v[166:169], v236 offset:49152
	ds_read_b128 v[170:173], v236 offset:50176
	ds_read_b128 v[174:177], v236 offset:51200
	ds_read_b128 v[178:181], v236 offset:52224
	ds_read_b128 v[194:197], v236 offset:53248
	ds_read_b128 v[198:201], v236 offset:54272
	ds_read_b128 v[202:205], v236 offset:55296
	ds_read_b128 v[206:209], v236 offset:56320
	global_load_lds_dwordx4 v[210:211], off
	s_add_i32 m0, s50, 0x2000
	s_add_u32 s50, s54, 0x160080
	v_lshl_add_u64 v[210:211], v[212:213], 0, s[28:29]
	s_addc_u32 s51, s55, 0
	s_add_i32 s54, s77, s59
	global_load_lds_dwordx4 v[210:211], off
	v_lshl_add_u64 v[210:211], s[50:51], 0, v[96:97]
	s_mov_b32 m0, s54
	s_nop 0
	global_load_lds_dwordx4 v[210:211], off
	v_lshl_add_u64 v[210:211], s[50:51], 0, v[98:99]
	s_add_i32 m0, s54, 0x2000
	s_nop 0
	global_load_lds_dwordx4 v[210:211], off
	v_lshl_add_u64 v[210:211], v[214:215], 0, s[28:29]
	s_mov_b32 m0, s63
	s_nop 0
	global_load_lds_dwordx4 v[210:211], off
	v_lshl_add_u64 v[210:211], v[216:217], 0, s[28:29]
	s_mov_b32 m0, s66
	s_nop 0
	global_load_lds_dwordx4 v[210:211], off
	s_waitcnt vmcnt(8)
	s_waitcnt lgkmcnt(0)
	v_mfma_f32_16x16x32_bf16 v[60:63], v[126:129], v[166:169], v[60:63]
	v_mfma_f32_16x16x32_bf16 v[56:59], v[142:145], v[166:169], v[56:59]
	v_mfma_f32_16x16x32_bf16 v[44:47], v[126:129], v[174:177], v[44:47]
	v_mfma_f32_16x16x32_bf16 v[40:43], v[142:145], v[174:177], v[40:43]
	s_setprio 1
	s_barrier
	v_mfma_f32_16x16x32_bf16 v[28:31], v[126:129], v[194:197], v[28:31]
	v_mfma_f32_16x16x32_bf16 v[24:27], v[142:145], v[194:197], v[24:27]
	v_mfma_f32_16x16x32_bf16 v[12:15], v[126:129], v[202:205], v[12:15]
	v_mfma_f32_16x16x32_bf16 v[8:11], v[142:145], v[202:205], v[8:11]
	v_mfma_f32_16x16x32_bf16 v[60:63], v[130:133], v[170:173], v[60:63]
	v_mfma_f32_16x16x32_bf16 v[56:59], v[146:149], v[170:173], v[56:59]
	v_mfma_f32_16x16x32_bf16 v[44:47], v[130:133], v[178:181], v[44:47]
	v_mfma_f32_16x16x32_bf16 v[40:43], v[146:149], v[178:181], v[40:43]
	v_mfma_f32_16x16x32_bf16 v[28:31], v[130:133], v[198:201], v[28:31]
	v_mfma_f32_16x16x32_bf16 v[24:27], v[146:149], v[198:201], v[24:27]
	v_mfma_f32_16x16x32_bf16 v[12:15], v[130:133], v[206:209], v[12:15]
	v_mfma_f32_16x16x32_bf16 v[8:11], v[146:149], v[206:209], v[8:11]
	v_mfma_f32_16x16x32_bf16 v[52:55], v[150:153], v[166:169], v[52:55]
	v_mfma_f32_16x16x32_bf16 v[48:51], v[158:161], v[166:169], v[48:51]
	v_mfma_f32_16x16x32_bf16 v[36:39], v[150:153], v[174:177], v[36:39]
	v_mfma_f32_16x16x32_bf16 v[32:35], v[158:161], v[174:177], v[32:35]
	v_mfma_f32_16x16x32_bf16 v[20:23], v[150:153], v[194:197], v[20:23]
	v_mfma_f32_16x16x32_bf16 v[16:19], v[158:161], v[194:197], v[16:19]
	v_mfma_f32_16x16x32_bf16 v[4:7], v[150:153], v[202:205], v[4:7]
	v_mfma_f32_16x16x32_bf16 v[0:3], v[158:161], v[202:205], v[0:3]
	v_mfma_f32_16x16x32_bf16 v[52:55], v[154:157], v[170:173], v[52:55]
	v_mfma_f32_16x16x32_bf16 v[48:51], v[162:165], v[170:173], v[48:51]
	v_mfma_f32_16x16x32_bf16 v[36:39], v[154:157], v[178:181], v[36:39]
	v_mfma_f32_16x16x32_bf16 v[32:35], v[162:165], v[178:181], v[32:35]
	v_mfma_f32_16x16x32_bf16 v[20:23], v[154:157], v[198:201], v[20:23]
	v_mfma_f32_16x16x32_bf16 v[16:19], v[162:165], v[198:201], v[16:19]
	v_mfma_f32_16x16x32_bf16 v[4:7], v[154:157], v[206:209], v[4:7]
	v_mfma_f32_16x16x32_bf16 v[0:3], v[162:165], v[206:209], v[0:3]
	s_barrier
	s_setprio 0
	s_add_i32 s75, s75, 2
	s_add_u32 s72, s72, 0x100
	s_addc_u32 s73, s73, 0
	s_cmpk_gt_u32 s75, 0x55
	s_mov_b64 s[50:51], s[52:53]
	s_cbranch_scc0 .LBB0_403
	v_and_b32_e32 v127, 64, v228
	v_xor_b32_e32 v126, 16, v228
	v_add_u32_e32 v127, 64, v127
	v_cmp_lt_i32_e32 vcc, v126, v127
	s_lshl_b32 s50, s70, 8
	v_lshl_add_u32 v198, s71, 8, v101
	v_cndmask_b32_e32 v126, v228, v126, vcc
	v_or_b32_e32 v194, s50, v235
	v_lshlrev_b32_e32 v238, 2, v126
	v_xor_b32_e32 v126, 32, v228
	v_or_b32_e32 v196, s50, v234
	v_ashrrev_i32_e32 v195, 31, v194
	v_cmp_lt_i32_e32 vcc, v126, v127
	v_ashrrev_i32_e32 v199, 31, v198
	v_ashrrev_i32_e32 v197, 31, v196
	v_cndmask_b32_e32 v126, v228, v126, vcc
	v_lshl_add_u64 v[202:203], s[34:35], 0, v[194:195]
	v_lshlrev_b64 v[216:217], 11, v[198:199]
	v_lshlrev_b32_e32 v237, 2, v126
	v_lshlrev_b64 v[218:219], 1, v[196:197]
	v_lshl_add_u64 v[126:127], v[202:203], 0, v[216:217]
	v_lshl_add_u64 v[200:201], s[30:31], 0, v[218:219]
	global_load_dwordx4 v[170:173], v[126:127], off
	v_lshlrev_b64 v[220:221], 12, v[198:199]
	v_lshl_add_u64 v[126:127], v[200:201], 0, v[220:221]
	global_load_dwordx4 v[178:181], v[126:127], off
	global_load_dwordx4 v[174:177], v[126:127], off offset:256
	v_or_b32_e32 v212, 16, v198
	v_ashrrev_i32_e32 v213, 31, v212
	v_lshlrev_b64 v[214:215], 11, v[212:213]
	v_lshl_add_u64 v[126:127], v[202:203], 0, v[214:215]
	v_or_b32_e32 v208, 32, v198
	global_load_dwordx4 v[158:161], v[126:127], off
	v_lshlrev_b64 v[126:127], 12, v[212:213]
	v_ashrrev_i32_e32 v209, 31, v208
	v_lshl_add_u64 v[126:127], v[200:201], 0, v[126:127]
	v_lshlrev_b64 v[210:211], 11, v[208:209]
	global_load_dwordx4 v[166:169], v[126:127], off
	global_load_dwordx4 v[162:165], v[126:127], off offset:256
	v_lshl_add_u64 v[126:127], v[202:203], 0, v[210:211]
	v_or_b32_e32 v204, 48, v198
	global_load_dwordx4 v[146:149], v[126:127], off
	v_lshlrev_b64 v[126:127], 12, v[208:209]
	v_ashrrev_i32_e32 v205, 31, v204
	v_lshl_add_u64 v[126:127], v[200:201], 0, v[126:127]
	v_lshlrev_b64 v[206:207], 11, v[204:205]
	v_lshlrev_b64 v[130:131], 12, v[204:205]
	global_load_dwordx4 v[154:157], v[126:127], off
	global_load_dwordx4 v[150:153], v[126:127], off offset:256
	v_lshl_add_u64 v[126:127], v[202:203], 0, v[206:207]
	v_lshl_add_u64 v[130:131], v[200:201], 0, v[130:131]
	global_load_dwordx4 v[126:129], v[126:127], off
	s_nop 0
	global_load_dwordx4 v[142:145], v[130:131], off
	s_nop 0
	global_load_dwordx4 v[130:133], v[130:131], off offset:256
	v_mov_b32_e32 v243, v136
	v_mov_b32_e32 v242, v140
	s_waitcnt vmcnt(0)
; #define PG8_GAS __attribute__((address_space(1)))
; __device__ __forceinline__ float e_x24(unsigned h16, unsigned l8) { return __uint_as_float(((h16 - (l8 >> 7)) << 16) | (l8 << 8)); }
;     __device__ __forceinline__ void operator()(const f32x4 (&acc)[2][2][4][2], const Unit& u, int wr, int wc, int fr, int fq) const {
;     ...
;             for (int m = 0; m < 4; ++m) {
;                 const int row = row0 + ai * HALF + m * 16; const size_t off = (size_t)row * 2048 + col0, loff = (size_t)row * 2048 + lcol; float ss = 0.f;
;                 const u32x4 l4 = L4[m];
;                 u32x4 lo4;
; #pragma unroll
;                 for (int bj = 0; bj < 2; ++bj) {
;                     const u32x4 h4 = H4[m][bj];
;                     u32x4 ho;
; #pragma unroll
;                     for (int j = 0; j < 4; ++j) {
;                         const unsigned lw = l4[2 * bj + (j >> 1)], lb0 = (lw >> (16 * (j & 1))) & 0xffu, lb1 = (lw >> (16 * (j & 1) + 8)) & 0xffu;
;                         const float x0 = e_x24(h4[j] & 0xffffu, lb0) + acc[ai][bj][m][j >> 1][2 * (j & 1)] * scale, x1 = e_x24(h4[j] >> 16, lb1) + acc[ai][bj][m][j >> 1][2 * (j & 1) + 1] * scale;
;                         const unsigned b0 = __float_as_uint(x0), b1 = __float_as_uint(x1);
;                         ho[j] = ((b0 + 0x8000u) >> 16) | ((b1 + 0x8000u) & 0xffff0000u);
;                         const unsigned nb = ((b0 >> 8) & 0xffu) | (b1 & 0xff00u);
;                         if ((j & 1) == 0) lo4[2 * bj + (j >> 1)] = nb; else lo4[2 * bj + (j >> 1)] |= nb << 16;
;                         ss += x0 * x0 + x1 * x1;
;                     }
;                     *(PG8_GAS u32x4*)(hout + off + bj * HALF) = ho;
;                 }
	v_lshrrev_b32_sdwa v222, v229, v171 dst_sel:DWORD dst_unused:UNUSED_PAD src0_sel:DWORD src1_sel:BYTE_0
	v_lshrrev_b32_sdwa v223, v229, v170 dst_sel:DWORD dst_unused:UNUSED_PAD src0_sel:DWORD src1_sel:BYTE_0
	v_sub_u32_sdwa v224, v178, v223 dst_sel:WORD_1 dst_unused:UNUSED_PAD src0_sel:DWORD src1_sel:DWORD
	v_sub_u32_sdwa v222, v180, v222 dst_sel:WORD_1 dst_unused:UNUSED_PAD src0_sel:DWORD src1_sel:DWORD
	v_lshlrev_b32_sdwa v223, v230, v171 dst_sel:DWORD dst_unused:UNUSED_PAD src0_sel:DWORD src1_sel:BYTE_0
	v_lshlrev_b32_sdwa v225, v230, v170 dst_sel:DWORD dst_unused:UNUSED_PAD src0_sel:DWORD src1_sel:BYTE_0
	v_or_b32_e32 v223, v222, v223
	v_or_b32_e32 v222, v224, v225
	v_mov_b32_e32 v224, v138
	v_mov_b32_e32 v225, v134
	v_pk_fma_f32 v[222:223], v[224:225], 0.5, v[222:223] op_sel_hi:[1,0,1]
	v_lshlrev_b32_e32 v224, 1, v170
	v_add_u32_e32 v134, 0x8000, v222
	v_lshrrev_b32_e32 v138, 16, v134
	v_lshlrev_b32_e32 v134, 1, v171
	v_and_b32_e32 v134, 0x10000, v134
	v_and_b32_e32 v224, 0x10000, v224
	v_sub_u32_e32 v134, v180, v134
	v_sub_u32_e32 v178, v178, v224
	v_and_b32_e32 v134, 0xffff0000, v134
	v_and_b32_e32 v178, 0xffff0000, v178
	v_and_b32_e32 v180, 0xff00, v171
	v_and_b32_e32 v224, 0xff00, v170
	v_or_b32_e32 v225, v134, v180
	v_or_b32_e32 v224, v178, v224
	v_mov_b32_e32 v134, v139
	v_pk_fma_f32 v[224:225], v[134:135], 0.5, v[224:225] op_sel_hi:[1,0,1]
	v_and_b32_sdwa v135, v171, s93 dst_sel:DWORD dst_unused:UNUSED_PAD src0_sel:WORD_1 src1_sel:DWORD
	v_and_b32_sdwa v178, v170, s93 dst_sel:DWORD dst_unused:UNUSED_PAD src0_sel:WORD_1 src1_sel:DWORD
	v_lshlrev_b32_sdwa v239, v231, v170 dst_sel:DWORD dst_unused:UNUSED_PAD src0_sel:DWORD src1_sel:BYTE_3
	v_lshlrev_b32_sdwa v136, v231, v171 dst_sel:DWORD dst_unused:UNUSED_PAD src0_sel:DWORD src1_sel:BYTE_3
	v_lshrrev_b32_e32 v180, 7, v178
	v_lshrrev_b32_e32 v240, 7, v135
	v_and_b32_e32 v136, 0x10000, v136
	v_and_b32_e32 v140, 0x10000, v239
	v_sub_u32_sdwa v180, v179, v180 dst_sel:WORD_1 dst_unused:UNUSED_PAD src0_sel:DWORD src1_sel:DWORD
	v_sub_u32_sdwa v240, v181, v240 dst_sel:WORD_1 dst_unused:UNUSED_PAD src0_sel:DWORD src1_sel:DWORD
	v_lshlrev_b32_e32 v135, 8, v135
	v_lshlrev_b32_e32 v178, 8, v178
	v_sub_u32_e32 v136, v181, v136
	v_sub_u32_e32 v140, v179, v140
	v_or_b32_e32 v241, v240, v135
	v_or_b32_e32 v240, v180, v178
	v_and_b32_e32 v136, 0xffff0000, v136
	v_and_b32_e32 v140, 0xffff0000, v140
	v_lshlrev_b32_sdwa v171, v230, v171 dst_sel:DWORD dst_unused:UNUSED_PAD src0_sel:DWORD src1_sel:BYTE_3
	v_lshlrev_b32_sdwa v170, v230, v170 dst_sel:DWORD dst_unused:UNUSED_PAD src0_sel:DWORD src1_sel:BYTE_3
	v_pk_fma_f32 v[240:241], v[242:243], 0.5, v[240:241] op_sel_hi:[1,0,1]
	v_or_b32_e32 v171, v136, v171
	v_or_b32_e32 v170, v140, v170
	v_mov_b32_e32 v136, v141
	v_add_u32_e32 v135, 0x8000, v240
	v_pk_fma_f32 v[140:141], v[136:137], 0.5, v[170:171] op_sel_hi:[1,0,1]
	v_lshrrev_b32_e32 v135, 16, v135
	v_add_u32_e32 v136, 0x8000, v140
	v_and_or_b32 v135, v136, s90, v135
	v_pk_mul_f32 v[136:137], v[140:141], v[140:141]
	v_add_u32_e32 v178, 0x8000, v141
	v_pk_fma_f32 v[170:171], v[240:241], v[240:241], v[136:137]
	v_add_u32_e32 v136, 0x8000, v223
	v_lshrrev_b32_e32 v136, 16, v136
	v_add_u32_e32 v137, 0x8000, v225
	v_and_or_b32 v136, v137, s90, v136
	v_add_u32_e32 v137, 0x8000, v241
	v_lshrrev_b32_e32 v137, 16, v137
	v_add_u32_e32 v134, 0x8000, v224
	v_and_or_b32 v137, v178, s90, v137
	v_lshl_add_u64 v[178:179], s[30:31], 0, v[220:221]
	v_and_or_b32 v134, v134, s90, v138
	v_lshl_add_u64 v[178:179], v[178:179], 0, v[218:219]
	global_store_dwordx4 v[178:179], v[134:137], off
	v_lshlrev_b32_sdwa v220, v231, v172 dst_sel:DWORD dst_unused:UNUSED_PAD src0_sel:DWORD src1_sel:BYTE_3
	v_mov_b32_e32 v219, v120
	v_lshrrev_b32_sdwa v134, v229, v173 dst_sel:DWORD dst_unused:UNUSED_PAD src0_sel:DWORD src1_sel:BYTE_0
	v_lshrrev_b32_sdwa v135, v229, v172 dst_sel:DWORD dst_unused:UNUSED_PAD src0_sel:DWORD src1_sel:BYTE_0
	v_sub_u32_sdwa v136, v174, v135 dst_sel:WORD_1 dst_unused:UNUSED_PAD src0_sel:DWORD src1_sel:DWORD
	v_sub_u32_sdwa v134, v176, v134 dst_sel:WORD_1 dst_unused:UNUSED_PAD src0_sel:DWORD src1_sel:DWORD
	v_lshlrev_b32_sdwa v135, v230, v173 dst_sel:DWORD dst_unused:UNUSED_PAD src0_sel:DWORD src1_sel:BYTE_0
	v_lshlrev_b32_sdwa v137, v230, v172 dst_sel:DWORD dst_unused:UNUSED_PAD src0_sel:DWORD src1_sel:BYTE_0
	v_or_b32_e32 v135, v134, v135
	v_or_b32_e32 v134, v136, v137
	v_mov_b32_e32 v136, v122
	v_mov_b32_e32 v137, v118
	v_pk_fma_f32 v[134:135], v[136:137], 0.5, v[134:135] op_sel_hi:[1,0,1]
; #define PG8_GAS __attribute__((address_space(1)))
; __device__ __forceinline__ float e_x24(unsigned h16, unsigned l8) { return __uint_as_float(((h16 - (l8 >> 7)) << 16) | (l8 << 8)); }
;     __device__ __forceinline__ void operator()(const f32x4 (&acc)[2][2][4][2], const Unit& u, int wr, int wc, int fr, int fq) const {
;     ...
;                         const float x0 = e_x24(h4[j] & 0xffffu, lb0) + acc[ai][bj][m][j >> 1][2 * (j & 1)] * scale, x1 = e_x24(h4[j] >> 16, lb1) + acc[ai][bj][m][j >> 1][2 * (j & 1) + 1] * scale;
;                         const unsigned b0 = __float_as_uint(x0), b1 = __float_as_uint(x1);
;                         ho[j] = ((b0 + 0x8000u) >> 16) | ((b1 + 0x8000u) & 0xffff0000u);
;                         const unsigned nb = ((b0 >> 8) & 0xffu) | (b1 & 0xff00u);
;                         if ((j & 1) == 0) lo4[2 * bj + (j >> 1)] = nb; else lo4[2 * bj + (j >> 1)] |= nb << 16;
;                         ss += x0 * x0 + x1 * x1;
;                     }
;                     *(PG8_GAS u32x4*)(hout + off + bj * HALF) = ho;
;                 }
;                 *(PG8_GAS u32x4*)(lout + loff) = lo4;
;                 ss += __shfl_xor(ss, 16); ss += __shfl_xor(ss, 32);
;                 if (fq == 0) __hip_atomic_fetch_add((PG8_GAS unsigned long long*)(rowsq_out + row), (unsigned long long)(ss * 16777216.0f + 0.5f), __ATOMIC_RELAXED, __HIP_MEMORY_SCOPE_AGENT);
	v_lshlrev_b32_e32 v122, 1, v172
	v_add_u32_e32 v118, 0x8000, v134
	v_lshrrev_b32_e32 v180, 16, v118
	v_lshlrev_b32_e32 v118, 1, v173
	v_and_b32_e32 v118, 0x10000, v118
	v_and_b32_e32 v122, 0x10000, v122
	v_sub_u32_e32 v118, v176, v118
	v_sub_u32_e32 v122, v174, v122
	v_and_b32_e32 v118, 0xffff0000, v118
	v_and_b32_e32 v122, 0xffff0000, v122
	v_and_b32_e32 v136, 0xff00, v173
	v_and_b32_e32 v174, 0xff00, v172
	v_or_b32_e32 v137, v118, v136
	v_or_b32_e32 v136, v122, v174
	v_mov_b32_e32 v118, v123
	v_pk_fma_f32 v[122:123], v[118:119], 0.5, v[136:137] op_sel_hi:[1,0,1]
	v_and_b32_sdwa v119, v173, s93 dst_sel:DWORD dst_unused:UNUSED_PAD src0_sel:WORD_1 src1_sel:DWORD
	v_add_u32_e32 v118, 0x8000, v122
	v_and_b32_sdwa v174, v172, s93 dst_sel:DWORD dst_unused:UNUSED_PAD src0_sel:WORD_1 src1_sel:DWORD
	v_lshlrev_b32_sdwa v120, v231, v173 dst_sel:DWORD dst_unused:UNUSED_PAD src0_sel:DWORD src1_sel:BYTE_3
	v_and_or_b32 v118, v118, s90, v180
	v_lshrrev_b32_e32 v176, 7, v174
	v_lshrrev_b32_e32 v180, 7, v119
	v_mov_b32_e32 v218, v124
	v_and_b32_e32 v120, 0x10000, v120
	v_and_b32_e32 v124, 0x10000, v220
	v_sub_u32_sdwa v176, v175, v176 dst_sel:WORD_1 dst_unused:UNUSED_PAD src0_sel:DWORD src1_sel:DWORD
	v_sub_u32_sdwa v180, v177, v180 dst_sel:WORD_1 dst_unused:UNUSED_PAD src0_sel:DWORD src1_sel:DWORD
	v_lshlrev_b32_e32 v119, 8, v119
	v_lshlrev_b32_e32 v174, 8, v174
	v_sub_u32_e32 v120, v177, v120
	v_sub_u32_e32 v124, v175, v124
	v_or_b32_e32 v181, v180, v119
	v_or_b32_e32 v180, v176, v174
	v_and_b32_e32 v120, 0xffff0000, v120
	v_and_b32_e32 v124, 0xffff0000, v124
	v_lshlrev_b32_sdwa v173, v230, v173 dst_sel:DWORD dst_unused:UNUSED_PAD src0_sel:DWORD src1_sel:BYTE_3
	v_lshlrev_b32_sdwa v172, v230, v172 dst_sel:DWORD dst_unused:UNUSED_PAD src0_sel:DWORD src1_sel:BYTE_3
	v_pk_fma_f32 v[180:181], v[218:219], 0.5, v[180:181] op_sel_hi:[1,0,1]
	v_or_b32_e32 v173, v120, v173
	v_or_b32_e32 v172, v124, v172
	v_mov_b32_e32 v120, v125
	v_add_u32_e32 v119, 0x8000, v180
	v_pk_fma_f32 v[124:125], v[120:121], 0.5, v[172:173] op_sel_hi:[1,0,1]
	v_lshrrev_b32_e32 v119, 16, v119
	v_add_u32_e32 v120, 0x8000, v124
	v_pk_mul_f32 v[138:139], v[224:225], v[224:225]
	v_pk_mul_f32 v[136:137], v[122:123], v[122:123]
	v_and_or_b32 v119, v120, s90, v119
	v_pk_mul_f32 v[120:121], v[124:125], v[124:125]
	v_pk_fma_f32 v[138:139], v[222:223], v[222:223], v[138:139]
	v_pk_fma_f32 v[136:137], v[134:135], v[134:135], v[136:137]
	v_pk_fma_f32 v[172:173], v[180:181], v[180:181], v[120:121]
	v_add_u32_e32 v120, 0x8000, v135
	v_lshrrev_b32_e32 v134, 8, v134
	v_lshrrev_b32_e32 v120, 16, v120
	v_add_u32_e32 v121, 0x8000, v123
	v_perm_b32 v122, v122, v134, s94
	v_add_f32_e32 v134, v138, v170
	v_and_or_b32 v120, v121, s90, v120
	v_add_u32_e32 v121, 0x8000, v181
	v_add_f32_e32 v134, v139, v134
	v_lshrrev_b32_e32 v121, 16, v121
	v_add_u32_e32 v174, 0x8000, v125
	v_add_f32_e32 v134, v171, v134
	v_and_or_b32 v121, v174, s90, v121
	v_lshrrev_b32_e32 v174, 8, v181
	v_lshrrev_b32_e32 v175, 8, v180
	v_add_f32_e32 v134, v136, v134
	v_lshrrev_b32_e32 v176, 8, v241
	v_lshrrev_b32_e32 v177, 8, v240
	v_perm_b32 v124, v124, v175, s94
	v_perm_b32 v125, v125, v174, s94
	v_lshrrev_b32_e32 v135, 8, v135
	v_lshrrev_b32_e32 v174, 8, v223
	v_lshrrev_b32_e32 v175, 8, v222
	v_add_f32_e32 v134, v172, v134
	v_perm_b32 v140, v140, v177, s94
	v_perm_b32 v141, v141, v176, s94
	v_perm_b32 v175, v224, v175, s94
	v_perm_b32 v174, v225, v174, s94
	v_perm_b32 v123, v123, v135, s94
	v_add_f32_e32 v134, v137, v134
	global_store_dwordx4 v[178:179], v[118:121], off offset:256
	v_lshl_or_b32 v125, v125, 16, v123
	v_lshl_or_b32 v124, v124, 16, v122
	v_lshl_add_u64 v[118:119], s[34:35], 0, v[216:217]
	v_lshl_or_b32 v123, v141, 16, v174
	v_lshl_or_b32 v122, v140, 16, v175
	v_add_f32_e32 v134, v173, v134
	v_lshl_add_u64 v[118:119], v[118:119], 0, v[194:195]
	global_store_dwordx4 v[118:119], v[122:125], off
	ds_bpermute_b32 v118, v238, v134
	s_waitcnt lgkmcnt(0)
	v_add_f32_e32 v118, v134, v118
	ds_bpermute_b32 v119, v237, v118
	s_and_saveexec_b64 s[50:51], s[40:41]
	s_cbranch_execz .LBB0_406
	s_waitcnt lgkmcnt(0)
	v_add_f32_e32 v118, v118, v119
	v_fma_f32 v118, v118, s80, 0.5
	v_trunc_f32_e32 v118, v118
	v_mul_f32_e32 v119, 0x2f800000, v118
	v_floor_f32_e32 v119, v119
	v_fmac_f32_e32 v118, 0xcf800000, v119
	v_cvt_u32_f32_e32 v118, v118
	v_cvt_u32_f32_e32 v119, v119
	v_lshl_add_u64 v[120:121], v[198:199], 3, s[48:49]
	global_atomic_add_x2 v[120:121], v[118:119], off

; #define PG8_STAGE(bufoff, gbase, voff) do { _Pragma("unroll") for (int _i = 0; _i < 2; ++_i) \
;         __builtin_amdgcn_global_load_lds((const unsigned*)((const char*)(gbase) + (voff)[_i]), (PG8_LAS unsigned*)(lds + (bufoff) + ldsw + _i * 8192), 16, 0, 0); } while (0)
; #define PG8_LDA(dst, b, h) do { _Pragma("unroll") for (int m = 0; m < 4; ++m) _Pragma("unroll") for (int k = 0; k < 2; ++k) dst[m][k] = *(const PG8_LAS bf16x8*)(lds + PG8_SA(b, h) + aoff + m * 2048 + k * 1024); } while (0)
; #define PG8_LDB(dst, b, h) do { _Pragma("unroll") for (int n = 0; n < 2; ++n) _Pragma("unroll") for (int k = 0; k < 2; ++k) dst[n][k] = *(const PG8_LAS bf16x8*)(lds + PG8_SB(b, h) + boff + n * 2048 + k * 1024); } while (0)
; #define PG8_MMA(ai, bj, At, Bt) do { __builtin_amdgcn_s_setprio(1); _Pragma("unroll") for (int m = 0; m < 4; ++m) _Pragma("unroll") for (int n = 0; n < 2; ++n) _Pragma("unroll") for (int k = 0; k < 2; ++k) \
;         acc[ai][bj][m][n] = __builtin_amdgcn_mfma_f32_16x16x32_bf16(Bt[n][k], At[m][k], acc[ai][bj][m][n], 0, 0, 0); __builtin_amdgcn_s_setprio(0); } while (0)
; #define PG8_WAIT_V(n) asm volatile("s_waitcnt vmcnt(" #n ")" ::: "memory")
; #define PG8_WAIT_L(n) asm volatile("s_waitcnt lgkmcnt(" #n ")" ::: "memory")
; template <class Epi, class Sched, bool ALIGN_EPI = false, bool SP2 = false>
; __device__ __forceinline__ void gemm_phase(PG8_LAS unsigned char* lds, const Gemm g, const Sched& S, const Epi& E, const int tid) {
;     ...
;             const bool last = (t == nt - 2);
;             const char* a1 = cA + (size_t)(t + 1) * kstep;
;             const char* a2 = last ? nA : cA + (size_t)(t + 2) * kstep; const char* b2 = last ? nB : cB + (size_t)(t + 2) * kstep;
;             const char* a3 = a2 + kstep; const char* b3 = b2 + kstep;
;             if (last && has_next) S.a_ready(nxt);
;             if constexpr (SP2) {
;             PG8_LDB(B0, 0, 0); PG8_LDB(B1, 0, 1); PG8_SCHED; PG8_LDA(At, 0, 0); PG8_STAGE(PG8_SA(1, 1), a1 + hstep, voffA);
;             PG8_WAIT_V(8); PG8_WAIT_L(0); PG8_BAR; PG8_MMA(0, 0, At, B0); PG8_MMA(0, 1, At, B1); PG8_BAR; PG8_SCHED;
;             PG8_LDA(At, 0, 1); PG8_STAGE(PG8_SB(0, 0), b2, voffB); PG8_STAGE(PG8_SB(0, 1), b2 + hstep, voffB); PG8_STAGE(PG8_SA(0, 0), a2, voffA);
;             PG8_WAIT_V(8); PG8_WAIT_L(0); PG8_BAR; PG8_MMA(1, 0, At, B0); PG8_MMA(1, 1, At, B1); PG8_BAR; PG8_SCHED;
.LBB0_488:
	s_add_u32 s58, s42, 0xfff80080
	s_addc_u32 s59, s43, -1
	s_add_i32 s78, 0, 0x10000
	s_cmp_eq_u32 s77, 28
	s_cselect_b32 s61, s53, s59
	s_cselect_b32 s60, s72, s58
	s_cselect_b32 s59, s51, s76
	s_cselect_b32 s58, s73, s75
	s_add_i32 s80, 0, 0x14000
	v_add_u32_e32 v156, s78, v163
	v_add_u32_e32 v160, s80, v163
	ds_read_b128 v[144:147], v156
	ds_read_b128 v[148:151], v156 offset:1024
	ds_read_b128 v[152:155], v156 offset:2048
	ds_read_b128 v[156:159], v156 offset:3072
	ds_read_b128 v[166:169], v160
	ds_read_b128 v[170:173], v160 offset:1024
	ds_read_b128 v[174:177], v160 offset:2048
	ds_read_b128 v[178:181], v160 offset:3072
	v_lshl_add_u64 v[160:161], s[42:43], 0, v[142:143]
	s_add_i32 m0, s63, 0xc000
	ds_read_b128 v[186:189], v165
	ds_read_b128 v[190:193], v165 offset:1024
	ds_read_b128 v[194:197], v165 offset:2048
	ds_read_b128 v[198:201], v165 offset:3072
	ds_read_b128 v[202:205], v165 offset:4096
	ds_read_b128 v[206:209], v165 offset:5120
	ds_read_b128 v[210:213], v165 offset:6144
	ds_read_b128 v[214:217], v165 offset:7168
	global_load_lds_dwordx4 v[160:161], off
	v_lshl_add_u64 v[160:161], s[42:43], 0, v[140:141]
	s_add_i32 m0, s63, 0xe000
	s_nop 0
	global_load_lds_dwordx4 v[160:161], off
	s_waitcnt vmcnt(8)
	s_waitcnt lgkmcnt(0)
	v_mfma_f32_16x16x32_bf16 v[122:125], v[144:147], v[186:189], v[122:125]
	v_mfma_f32_16x16x32_bf16 v[118:121], v[152:155], v[186:189], v[118:121]
	v_mfma_f32_16x16x32_bf16 v[110:113], v[144:147], v[194:197], v[110:113]
	v_mfma_f32_16x16x32_bf16 v[106:109], v[152:155], v[194:197], v[106:109]
	s_setprio 1
	s_barrier
	v_mfma_f32_16x16x32_bf16 v[88:91], v[144:147], v[202:205], v[88:91]
	v_mfma_f32_16x16x32_bf16 v[84:87], v[152:155], v[202:205], v[84:87]
	v_mfma_f32_16x16x32_bf16 v[72:75], v[144:147], v[210:213], v[72:75]
	v_mfma_f32_16x16x32_bf16 v[68:71], v[152:155], v[210:213], v[68:71]
	v_mfma_f32_16x16x32_bf16 v[122:125], v[148:151], v[190:193], v[122:125]
	v_mfma_f32_16x16x32_bf16 v[118:121], v[156:159], v[190:193], v[118:121]
	v_mfma_f32_16x16x32_bf16 v[110:113], v[148:151], v[198:201], v[110:113]
	v_mfma_f32_16x16x32_bf16 v[106:109], v[156:159], v[198:201], v[106:109]
	v_mfma_f32_16x16x32_bf16 v[88:91], v[148:151], v[206:209], v[88:91]
	v_mfma_f32_16x16x32_bf16 v[84:87], v[156:159], v[206:209], v[84:87]
	v_mfma_f32_16x16x32_bf16 v[72:75], v[148:151], v[214:217], v[72:75]
	v_mfma_f32_16x16x32_bf16 v[68:71], v[156:159], v[214:217], v[68:71]
	v_mfma_f32_16x16x32_bf16 v[130:133], v[166:169], v[186:189], v[130:133]
	v_mfma_f32_16x16x32_bf16 v[126:129], v[174:177], v[186:189], v[126:129]
	v_mfma_f32_16x16x32_bf16 v[114:117], v[166:169], v[194:197], v[114:117]
	v_mfma_f32_16x16x32_bf16 v[102:105], v[174:177], v[194:197], v[102:105]
	v_mfma_f32_16x16x32_bf16 v[92:95], v[166:169], v[202:205], v[92:95]
	v_mfma_f32_16x16x32_bf16 v[80:83], v[174:177], v[202:205], v[80:83]
	v_mfma_f32_16x16x32_bf16 v[76:79], v[166:169], v[210:213], v[76:79]
	v_mfma_f32_16x16x32_bf16 v[64:67], v[174:177], v[210:213], v[64:67]
	v_mfma_f32_16x16x32_bf16 v[130:133], v[170:173], v[190:193], v[130:133]
	v_mfma_f32_16x16x32_bf16 v[126:129], v[178:181], v[190:193], v[126:129]
	v_mfma_f32_16x16x32_bf16 v[114:117], v[170:173], v[198:201], v[114:117]
	v_mfma_f32_16x16x32_bf16 v[102:105], v[178:181], v[198:201], v[102:105]
	v_mfma_f32_16x16x32_bf16 v[92:95], v[170:173], v[206:209], v[92:95]
	v_mfma_f32_16x16x32_bf16 v[80:83], v[178:181], v[206:209], v[80:83]
	v_mfma_f32_16x16x32_bf16 v[76:79], v[170:173], v[214:217], v[76:79]
	v_mfma_f32_16x16x32_bf16 v[64:67], v[178:181], v[214:217], v[64:67]
	s_barrier
	s_setprio 0
	s_add_i32 s78, s78, s62
	v_lshl_add_u64 v[160:161], s[58:59], 0, v[96:97]
	s_mov_b32 m0, s78
	ds_read_b128 v[186:189], v165 offset:16384
	ds_read_b128 v[190:193], v165 offset:17408
	ds_read_b128 v[194:197], v165 offset:18432
	ds_read_b128 v[198:201], v165 offset:19456
	ds_read_b128 v[202:205], v165 offset:20480
	ds_read_b128 v[206:209], v165 offset:21504
	ds_read_b128 v[210:213], v165 offset:22528
	ds_read_b128 v[214:217], v165 offset:23552
	global_load_lds_dwordx4 v[160:161], off
	s_add_i32 m0, s78, 0x2000
	s_add_u32 s78, s58, 0x80000
	v_lshl_add_u64 v[218:219], s[58:59], 0, v[98:99]
	s_addc_u32 s79, s59, 0
	s_add_i32 s80, s80, s62
	global_load_lds_dwordx4 v[218:219], off
	v_lshl_add_u64 v[220:221], s[78:79], 0, v[96:97]
	s_mov_b32 m0, s80
	v_lshl_add_u64 v[222:223], s[60:61], 0, v[134:135]
	global_load_lds_dwordx4 v[220:221], off
	v_lshl_add_u64 v[220:221], s[78:79], 0, v[98:99]
	s_add_i32 m0, s80, 0x2000
	s_nop 0
	global_load_lds_dwordx4 v[220:221], off
	v_lshl_add_u64 v[220:221], s[60:61], 0, v[136:137]
	s_mov_b32 m0, s63
	s_nop 0
	global_load_lds_dwordx4 v[220:221], off
	s_mov_b32 m0, s64
	s_nop 0
	global_load_lds_dwordx4 v[222:223], off
	s_waitcnt vmcnt(8)
	s_waitcnt lgkmcnt(0)
	v_mfma_f32_16x16x32_bf16 v[56:59], v[144:147], v[186:189], v[56:59]
	v_mfma_f32_16x16x32_bf16 v[52:55], v[152:155], v[186:189], v[52:55]
	v_mfma_f32_16x16x32_bf16 v[40:43], v[144:147], v[194:197], v[40:43]
	v_mfma_f32_16x16x32_bf16 v[36:39], v[152:155], v[194:197], v[36:39]
	s_setprio 1
	s_barrier
; #define PG8_STAGE(bufoff, gbase, voff) do { _Pragma("unroll") for (int _i = 0; _i < 2; ++_i) \
;         __builtin_amdgcn_global_load_lds((const unsigned*)((const char*)(gbase) + (voff)[_i]), (PG8_LAS unsigned*)(lds + (bufoff) + ldsw + _i * 8192), 16, 0, 0); } while (0)
; #define PG8_LDA(dst, b, h) do { _Pragma("unroll") for (int m = 0; m < 4; ++m) _Pragma("unroll") for (int k = 0; k < 2; ++k) dst[m][k] = *(const PG8_LAS bf16x8*)(lds + PG8_SA(b, h) + aoff + m * 2048 + k * 1024); } while (0)
; #define PG8_LDB(dst, b, h) do { _Pragma("unroll") for (int n = 0; n < 2; ++n) _Pragma("unroll") for (int k = 0; k < 2; ++k) dst[n][k] = *(const PG8_LAS bf16x8*)(lds + PG8_SB(b, h) + boff + n * 2048 + k * 1024); } while (0)
; #define PG8_MMA(ai, bj, At, Bt) do { __builtin_amdgcn_s_setprio(1); _Pragma("unroll") for (int m = 0; m < 4; ++m) _Pragma("unroll") for (int n = 0; n < 2; ++n) _Pragma("unroll") for (int k = 0; k < 2; ++k) \
;         acc[ai][bj][m][n] = __builtin_amdgcn_mfma_f32_16x16x32_bf16(Bt[n][k], At[m][k], acc[ai][bj][m][n], 0, 0, 0); __builtin_amdgcn_s_setprio(0); } while (0)
; #define PG8_WAIT_V(n) asm volatile("s_waitcnt vmcnt(" #n ")" ::: "memory")
; #define PG8_WAIT_L(n) asm volatile("s_waitcnt lgkmcnt(" #n ")" ::: "memory")
; #define PG8_BAR __builtin_amdgcn_s_barrier()
; #define PG8_SCHED __builtin_amdgcn_sched_barrier(0)
; template <class Epi, class Sched, bool ALIGN_EPI = false, bool SP2 = false>
; __device__ __forceinline__ void gemm_phase(PG8_LAS unsigned char* lds, const Gemm g, const Sched& S, const Epi& E, const int tid) {
;     ...
;             PG8_WAIT_V(8); PG8_WAIT_L(0); PG8_BAR; PG8_MMA(1, 0, At, B0); PG8_MMA(1, 1, At, B1); PG8_BAR; PG8_SCHED;
;             PG8_LDB(B0, 1, 0); PG8_LDB(B1, 1, 1); PG8_SCHED; PG8_LDA(At, 1, 0); PG8_STAGE(PG8_SA(0, 1), a2 + hstep, voffA);
;             PG8_WAIT_V(8); PG8_WAIT_L(0); PG8_BAR; PG8_MMA(0, 0, At, B0); PG8_MMA(0, 1, At, B1); PG8_BAR; PG8_SCHED;
	v_mfma_f32_16x16x32_bf16 v[24:27], v[144:147], v[202:205], v[24:27]
	v_mfma_f32_16x16x32_bf16 v[20:23], v[152:155], v[202:205], v[20:23]
	v_mfma_f32_16x16x32_bf16 v[8:11], v[144:147], v[210:213], v[8:11]
	v_mfma_f32_16x16x32_bf16 v[4:7], v[152:155], v[210:213], v[4:7]
	v_mfma_f32_16x16x32_bf16 v[56:59], v[148:151], v[190:193], v[56:59]
	v_mfma_f32_16x16x32_bf16 v[52:55], v[156:159], v[190:193], v[52:55]
	v_mfma_f32_16x16x32_bf16 v[40:43], v[148:151], v[198:201], v[40:43]
	v_mfma_f32_16x16x32_bf16 v[36:39], v[156:159], v[198:201], v[36:39]
	v_mfma_f32_16x16x32_bf16 v[24:27], v[148:151], v[206:209], v[24:27]
	v_mfma_f32_16x16x32_bf16 v[20:23], v[156:159], v[206:209], v[20:23]
	v_mfma_f32_16x16x32_bf16 v[8:11], v[148:151], v[214:217], v[8:11]
	v_mfma_f32_16x16x32_bf16 v[4:7], v[156:159], v[214:217], v[4:7]
	v_mfma_f32_16x16x32_bf16 v[60:63], v[166:169], v[186:189], v[60:63]
	v_mfma_f32_16x16x32_bf16 v[48:51], v[174:177], v[186:189], v[48:51]
	v_mfma_f32_16x16x32_bf16 v[44:47], v[166:169], v[194:197], v[44:47]
	v_mfma_f32_16x16x32_bf16 v[32:35], v[174:177], v[194:197], v[32:35]
	v_mfma_f32_16x16x32_bf16 v[28:31], v[166:169], v[202:205], v[28:31]
	v_mfma_f32_16x16x32_bf16 v[16:19], v[174:177], v[202:205], v[16:19]
	v_mfma_f32_16x16x32_bf16 v[12:15], v[166:169], v[210:213], v[12:15]
	v_mfma_f32_16x16x32_bf16 v[0:3], v[174:177], v[210:213], v[0:3]
	v_mfma_f32_16x16x32_bf16 v[60:63], v[170:173], v[190:193], v[60:63]
	v_mfma_f32_16x16x32_bf16 v[48:51], v[178:181], v[190:193], v[48:51]
	v_mfma_f32_16x16x32_bf16 v[44:47], v[170:173], v[198:201], v[44:47]
	v_mfma_f32_16x16x32_bf16 v[32:35], v[178:181], v[198:201], v[32:35]
	v_mfma_f32_16x16x32_bf16 v[28:31], v[170:173], v[206:209], v[28:31]
	v_mfma_f32_16x16x32_bf16 v[16:19], v[178:181], v[206:209], v[16:19]
	v_mfma_f32_16x16x32_bf16 v[12:15], v[170:173], v[214:217], v[12:15]
	v_mfma_f32_16x16x32_bf16 v[0:3], v[178:181], v[214:217], v[0:3]
	s_barrier
	s_setprio 0
	s_add_i32 s78, 0, 0x18000
	s_add_i32 s79, 0, 0x1c000
	v_add_u32_e32 v156, s78, v163
	v_add_u32_e32 v162, s79, v163
	ds_read_b128 v[144:147], v156
	ds_read_b128 v[148:151], v156 offset:1024
	ds_read_b128 v[152:155], v156 offset:2048
	ds_read_b128 v[156:159], v156 offset:3072
	ds_read_b128 v[166:169], v162
	ds_read_b128 v[170:173], v162 offset:1024
	ds_read_b128 v[174:177], v162 offset:2048
	ds_read_b128 v[178:181], v162 offset:3072
	s_add_u32 s60, s60, 0x80000
	s_addc_u32 s61, s61, 0
	s_mov_b32 m0, s65
	v_lshl_add_u64 v[224:225], s[60:61], 0, v[136:137]
	ds_read_b128 v[186:189], v165 offset:32768
	ds_read_b128 v[190:193], v165 offset:33792
	ds_read_b128 v[194:197], v165 offset:34816
	ds_read_b128 v[198:201], v165 offset:35840
	ds_read_b128 v[202:205], v165 offset:36864
	ds_read_b128 v[206:209], v165 offset:37888
	ds_read_b128 v[210:213], v165 offset:38912
	ds_read_b128 v[214:217], v165 offset:39936
	global_load_lds_dwordx4 v[224:225], off
	v_lshl_add_u64 v[224:225], s[60:61], 0, v[134:135]
	s_mov_b32 m0, s66
	s_nop 0
	global_load_lds_dwordx4 v[224:225], off
	s_waitcnt vmcnt(8)
	s_waitcnt lgkmcnt(0)
	v_mfma_f32_16x16x32_bf16 v[122:125], v[144:147], v[186:189], v[122:125]
	v_mfma_f32_16x16x32_bf16 v[118:121], v[152:155], v[186:189], v[118:121]
	v_mfma_f32_16x16x32_bf16 v[110:113], v[144:147], v[194:197], v[110:113]
	v_mfma_f32_16x16x32_bf16 v[106:109], v[152:155], v[194:197], v[106:109]
	s_setprio 1
	s_barrier
	v_mfma_f32_16x16x32_bf16 v[88:91], v[144:147], v[202:205], v[88:91]
	v_mfma_f32_16x16x32_bf16 v[84:87], v[152:155], v[202:205], v[84:87]
	v_mfma_f32_16x16x32_bf16 v[72:75], v[144:147], v[210:213], v[72:75]
	v_mfma_f32_16x16x32_bf16 v[68:71], v[152:155], v[210:213], v[68:71]
	v_mfma_f32_16x16x32_bf16 v[122:125], v[148:151], v[190:193], v[122:125]
	v_mfma_f32_16x16x32_bf16 v[118:121], v[156:159], v[190:193], v[118:121]
	v_mfma_f32_16x16x32_bf16 v[110:113], v[148:151], v[198:201], v[110:113]
	v_mfma_f32_16x16x32_bf16 v[106:109], v[156:159], v[198:201], v[106:109]
	v_mfma_f32_16x16x32_bf16 v[88:91], v[148:151], v[206:209], v[88:91]
	v_mfma_f32_16x16x32_bf16 v[84:87], v[156:159], v[206:209], v[84:87]
	v_mfma_f32_16x16x32_bf16 v[72:75], v[148:151], v[214:217], v[72:75]
	v_mfma_f32_16x16x32_bf16 v[68:71], v[156:159], v[214:217], v[68:71]
	v_mfma_f32_16x16x32_bf16 v[130:133], v[166:169], v[186:189], v[130:133]
	v_mfma_f32_16x16x32_bf16 v[126:129], v[174:177], v[186:189], v[126:129]
	v_mfma_f32_16x16x32_bf16 v[114:117], v[166:169], v[194:197], v[114:117]
	v_mfma_f32_16x16x32_bf16 v[102:105], v[174:177], v[194:197], v[102:105]
	v_mfma_f32_16x16x32_bf16 v[92:95], v[166:169], v[202:205], v[92:95]
	v_mfma_f32_16x16x32_bf16 v[80:83], v[174:177], v[202:205], v[80:83]
	v_mfma_f32_16x16x32_bf16 v[76:79], v[166:169], v[210:213], v[76:79]
	v_mfma_f32_16x16x32_bf16 v[64:67], v[174:177], v[210:213], v[64:67]
	v_mfma_f32_16x16x32_bf16 v[130:133], v[170:173], v[190:193], v[130:133]
	v_mfma_f32_16x16x32_bf16 v[126:129], v[178:181], v[190:193], v[126:129]
	v_mfma_f32_16x16x32_bf16 v[114:117], v[170:173], v[198:201], v[114:117]
	v_mfma_f32_16x16x32_bf16 v[102:105], v[178:181], v[198:201], v[102:105]
	v_mfma_f32_16x16x32_bf16 v[92:95], v[170:173], v[206:209], v[92:95]
	v_mfma_f32_16x16x32_bf16 v[80:83], v[178:181], v[206:209], v[80:83]
	v_mfma_f32_16x16x32_bf16 v[76:79], v[170:173], v[214:217], v[76:79]
	v_mfma_f32_16x16x32_bf16 v[64:67], v[178:181], v[214:217], v[64:67]
	s_barrier
; #define PG8_STAGE(bufoff, gbase, voff) do { _Pragma("unroll") for (int _i = 0; _i < 2; ++_i) \
;         __builtin_amdgcn_global_load_lds((const unsigned*)((const char*)(gbase) + (voff)[_i]), (PG8_LAS unsigned*)(lds + (bufoff) + ldsw + _i * 8192), 16, 0, 0); } while (0)
; #define PG8_LDA(dst, b, h) do { _Pragma("unroll") for (int m = 0; m < 4; ++m) _Pragma("unroll") for (int k = 0; k < 2; ++k) dst[m][k] = *(const PG8_LAS bf16x8*)(lds + PG8_SA(b, h) + aoff + m * 2048 + k * 1024); } while (0)
; #define PG8_MMA(ai, bj, At, Bt) do { __builtin_amdgcn_s_setprio(1); _Pragma("unroll") for (int m = 0; m < 4; ++m) _Pragma("unroll") for (int n = 0; n < 2; ++n) _Pragma("unroll") for (int k = 0; k < 2; ++k) \
;         acc[ai][bj][m][n] = __builtin_amdgcn_mfma_f32_16x16x32_bf16(Bt[n][k], At[m][k], acc[ai][bj][m][n], 0, 0, 0); __builtin_amdgcn_s_setprio(0); } while (0)
; #define PG8_WAIT_V(n) asm volatile("s_waitcnt vmcnt(" #n ")" ::: "memory")
; #define PG8_WAIT_L(n) asm volatile("s_waitcnt lgkmcnt(" #n ")" ::: "memory")
; #define PG8_BAR __builtin_amdgcn_s_barrier()
; #define PG8_SCHED __builtin_amdgcn_sched_barrier(0)
; template <class Epi, class Sched, bool ALIGN_EPI = false, bool SP2 = false>
; __device__ __forceinline__ void gemm_phase(PG8_LAS unsigned char* lds, const Gemm g, const Sched& S, const Epi& E, const int tid) {
;     ...
;             PG8_LDA(At, 1, 1); PG8_STAGE(PG8_SB(1, 0), b3, voffB); PG8_STAGE(PG8_SB(1, 1), b3 + hstep, voffB); PG8_STAGE(PG8_SA(1, 0), a3, voffA);
;             PG8_WAIT_V(8); PG8_WAIT_L(0); PG8_BAR; PG8_MMA(1, 0, At, B0); PG8_MMA(1, 1, At, B1); PG8_BAR; PG8_SCHED;
;     ...
;         if constexpr (ALIGN_EPI) { if (wr == 0) PG8_BAR; }
	s_setprio 0
	s_add_i32 s60, s78, s62
	v_lshl_add_u64 v[160:161], v[160:161], 0, s[28:29]
	s_mov_b32 m0, s60
	ds_read_b128 v[186:189], v165 offset:49152
	ds_read_b128 v[190:193], v165 offset:50176
	ds_read_b128 v[194:197], v165 offset:51200
	ds_read_b128 v[198:201], v165 offset:52224
	ds_read_b128 v[202:205], v165 offset:53248
	ds_read_b128 v[206:209], v165 offset:54272
	ds_read_b128 v[210:213], v165 offset:55296
	ds_read_b128 v[214:217], v165 offset:56320
	global_load_lds_dwordx4 v[160:161], off
	s_add_i32 m0, s60, 0x2000
	s_add_u32 s58, s58, 0x80080
	v_lshl_add_u64 v[160:161], v[218:219], 0, s[28:29]
	s_addc_u32 s59, s59, 0
	s_add_i32 s60, s79, s62
	global_load_lds_dwordx4 v[160:161], off
	v_lshl_add_u64 v[160:161], s[58:59], 0, v[96:97]
	s_mov_b32 m0, s60
	s_nop 0
	global_load_lds_dwordx4 v[160:161], off
	v_lshl_add_u64 v[160:161], s[58:59], 0, v[98:99]
	s_add_i32 m0, s60, 0x2000
	s_nop 0
	global_load_lds_dwordx4 v[160:161], off
	v_lshl_add_u64 v[160:161], v[220:221], 0, s[28:29]
	s_mov_b32 m0, s67
	s_nop 0
	global_load_lds_dwordx4 v[160:161], off
	v_lshl_add_u64 v[160:161], v[222:223], 0, s[28:29]
	s_mov_b32 m0, s68
	s_nop 0
	global_load_lds_dwordx4 v[160:161], off
	s_waitcnt vmcnt(8)
	s_waitcnt lgkmcnt(0)
	v_mfma_f32_16x16x32_bf16 v[56:59], v[144:147], v[186:189], v[56:59]
	v_mfma_f32_16x16x32_bf16 v[52:55], v[152:155], v[186:189], v[52:55]
	v_mfma_f32_16x16x32_bf16 v[40:43], v[144:147], v[194:197], v[40:43]
	v_mfma_f32_16x16x32_bf16 v[36:39], v[152:155], v[194:197], v[36:39]
	s_setprio 1
	s_barrier
	v_mfma_f32_16x16x32_bf16 v[24:27], v[144:147], v[202:205], v[24:27]
	v_mfma_f32_16x16x32_bf16 v[20:23], v[152:155], v[202:205], v[20:23]
	v_mfma_f32_16x16x32_bf16 v[8:11], v[144:147], v[210:213], v[8:11]
	v_mfma_f32_16x16x32_bf16 v[4:7], v[152:155], v[210:213], v[4:7]
	v_mfma_f32_16x16x32_bf16 v[56:59], v[148:151], v[190:193], v[56:59]
	v_mfma_f32_16x16x32_bf16 v[52:55], v[156:159], v[190:193], v[52:55]
	v_mfma_f32_16x16x32_bf16 v[40:43], v[148:151], v[198:201], v[40:43]
	v_mfma_f32_16x16x32_bf16 v[36:39], v[156:159], v[198:201], v[36:39]
	v_mfma_f32_16x16x32_bf16 v[24:27], v[148:151], v[206:209], v[24:27]
	v_mfma_f32_16x16x32_bf16 v[20:23], v[156:159], v[206:209], v[20:23]
	v_mfma_f32_16x16x32_bf16 v[8:11], v[148:151], v[214:217], v[8:11]
	v_mfma_f32_16x16x32_bf16 v[4:7], v[156:159], v[214:217], v[4:7]
	v_mfma_f32_16x16x32_bf16 v[60:63], v[166:169], v[186:189], v[60:63]
	v_mfma_f32_16x16x32_bf16 v[48:51], v[174:177], v[186:189], v[48:51]
	v_mfma_f32_16x16x32_bf16 v[44:47], v[166:169], v[194:197], v[44:47]
	v_mfma_f32_16x16x32_bf16 v[32:35], v[174:177], v[194:197], v[32:35]
	v_mfma_f32_16x16x32_bf16 v[28:31], v[166:169], v[202:205], v[28:31]
	v_mfma_f32_16x16x32_bf16 v[16:19], v[174:177], v[202:205], v[16:19]
	v_mfma_f32_16x16x32_bf16 v[12:15], v[166:169], v[210:213], v[12:15]
	v_mfma_f32_16x16x32_bf16 v[0:3], v[174:177], v[210:213], v[0:3]
	v_mfma_f32_16x16x32_bf16 v[60:63], v[170:173], v[190:193], v[60:63]
	v_mfma_f32_16x16x32_bf16 v[48:51], v[178:181], v[190:193], v[48:51]
	v_mfma_f32_16x16x32_bf16 v[44:47], v[170:173], v[198:201], v[44:47]
	v_mfma_f32_16x16x32_bf16 v[32:35], v[178:181], v[198:201], v[32:35]
	v_mfma_f32_16x16x32_bf16 v[28:31], v[170:173], v[206:209], v[28:31]
	v_mfma_f32_16x16x32_bf16 v[16:19], v[178:181], v[206:209], v[16:19]
	v_mfma_f32_16x16x32_bf16 v[12:15], v[170:173], v[214:217], v[12:15]
	v_mfma_f32_16x16x32_bf16 v[0:3], v[178:181], v[214:217], v[0:3]
	s_barrier
	s_setprio 0
	s_add_i32 s77, s77, 2
	s_add_u32 s75, s75, 0x100
	s_addc_u32 s76, s76, 0
	s_add_u32 s42, s42, 0x100
	s_addc_u32 s43, s43, 0
	s_cmp_gt_u32 s77, 29
	s_cbranch_scc0 .LBB0_488
	s_and_b64 vcc, exec, s[46:47]
	s_cbranch_vccz .LBB0_491
	s_barrier

; #define PG8_STAGE(bufoff, gbase, voff) do { _Pragma("unroll") for (int _i = 0; _i < 2; ++_i) \
;         __builtin_amdgcn_global_load_lds((const unsigned*)((const char*)(gbase) + (voff)[_i]), (PG8_LAS unsigned*)(lds + (bufoff) + ldsw + _i * 8192), 16, 0, 0); } while (0)
; #define PG8_LDA(dst, b, h) do { _Pragma("unroll") for (int m = 0; m < 4; ++m) _Pragma("unroll") for (int k = 0; k < 2; ++k) dst[m][k] = *(const PG8_LAS bf16x8*)(lds + PG8_SA(b, h) + aoff + m * 2048 + k * 1024); } while (0)
; #define PG8_LDB(dst, b, h) do { _Pragma("unroll") for (int n = 0; n < 2; ++n) _Pragma("unroll") for (int k = 0; k < 2; ++k) dst[n][k] = *(const PG8_LAS bf16x8*)(lds + PG8_SB(b, h) + boff + n * 2048 + k * 1024); } while (0)
; #define PG8_MMA(ai, bj, At, Bt) do { __builtin_amdgcn_s_setprio(1); _Pragma("unroll") for (int m = 0; m < 4; ++m) _Pragma("unroll") for (int n = 0; n < 2; ++n) _Pragma("unroll") for (int k = 0; k < 2; ++k) \
;         acc[ai][bj][m][n] = __builtin_amdgcn_mfma_f32_16x16x32_bf16(Bt[n][k], At[m][k], acc[ai][bj][m][n], 0, 0, 0); __builtin_amdgcn_s_setprio(0); } while (0)
; #define PG8_WAIT_V(n) asm volatile("s_waitcnt vmcnt(" #n ")" ::: "memory")
; #define PG8_WAIT_L(n) asm volatile("s_waitcnt lgkmcnt(" #n ")" ::: "memory")
; template <class Epi, class Sched, bool ALIGN_EPI = false, bool SP2 = false>
; __device__ __forceinline__ void gemm_phase(PG8_LAS unsigned char* lds, const Gemm g, const Sched& S, const Epi& E, const int tid) {
;     ...
;             const bool last = (t == nt - 2);
;             const char* a1 = cA + (size_t)(t + 1) * kstep;
;             const char* a2 = last ? nA : cA + (size_t)(t + 2) * kstep; const char* b2 = last ? nB : cB + (size_t)(t + 2) * kstep;
;             const char* a3 = a2 + kstep; const char* b3 = b2 + kstep;
;             if (last && has_next) S.a_ready(nxt);
;             if constexpr (SP2) {
;             PG8_LDB(B0, 0, 0); PG8_LDB(B1, 0, 1); PG8_SCHED; PG8_LDA(At, 0, 0); PG8_STAGE(PG8_SA(1, 1), a1 + hstep, voffA);
;             PG8_WAIT_V(8); PG8_WAIT_L(0); PG8_BAR; PG8_MMA(0, 0, At, B0); PG8_MMA(0, 1, At, B1); PG8_BAR; PG8_SCHED;
;             PG8_LDA(At, 0, 1); PG8_STAGE(PG8_SB(0, 0), b2, voffB); PG8_STAGE(PG8_SB(0, 1), b2 + hstep, voffB); PG8_STAGE(PG8_SA(0, 0), a2, voffA);
;             PG8_WAIT_V(8); PG8_WAIT_L(0); PG8_BAR; PG8_MMA(1, 0, At, B0); PG8_MMA(1, 1, At, B1); PG8_BAR; PG8_SCHED;
.LBB0_1199:
	s_add_u32 s56, s54, 0xfff80080
	s_addc_u32 s57, s55, -1
	s_add_i32 s77, 0, 0x10000
	s_cmp_eq_u32 s76, 28
	s_cselect_b32 s59, s49, s57
	s_cselect_b32 s58, s71, s56
	s_cselect_b32 s57, s47, s75
	s_cselect_b32 s56, s72, s73
	s_add_i32 s80, 0, 0x14000
	v_add_u32_e32 v146, s77, v233
	v_add_u32_e32 v162, s80, v233
	ds_read_b128 v[126:129], v146
	ds_read_b128 v[130:133], v146 offset:1024
	ds_read_b128 v[142:145], v146 offset:2048
	ds_read_b128 v[146:149], v146 offset:3072
	ds_read_b128 v[150:153], v162
	ds_read_b128 v[154:157], v162 offset:1024
	ds_read_b128 v[158:161], v162 offset:2048
	ds_read_b128 v[162:165], v162 offset:3072
	v_lshl_add_u64 v[210:211], s[54:55], 0, v[192:193]
	s_add_i32 m0, s62, 0xc000
	ds_read_b128 v[166:169], v236
	ds_read_b128 v[170:173], v236 offset:1024
	ds_read_b128 v[174:177], v236 offset:2048
	ds_read_b128 v[178:181], v236 offset:3072
	ds_read_b128 v[194:197], v236 offset:4096
	ds_read_b128 v[198:201], v236 offset:5120
	ds_read_b128 v[202:205], v236 offset:6144
	ds_read_b128 v[206:209], v236 offset:7168
	global_load_lds_dwordx4 v[210:211], off
	v_lshl_add_u64 v[210:211], s[54:55], 0, v[190:191]
	s_add_i32 m0, s62, 0xe000
	s_nop 0
	global_load_lds_dwordx4 v[210:211], off
	s_waitcnt vmcnt(8)
	s_waitcnt lgkmcnt(0)
	v_mfma_f32_16x16x32_bf16 v[138:141], v[126:129], v[166:169], v[138:141]
	v_mfma_f32_16x16x32_bf16 v[134:137], v[142:145], v[166:169], v[134:137]
	v_mfma_f32_16x16x32_bf16 v[114:117], v[126:129], v[174:177], v[114:117]
	v_mfma_f32_16x16x32_bf16 v[110:113], v[142:145], v[174:177], v[110:113]
	s_setprio 1
	s_barrier
	v_mfma_f32_16x16x32_bf16 v[92:95], v[126:129], v[194:197], v[92:95]
	v_mfma_f32_16x16x32_bf16 v[88:91], v[142:145], v[194:197], v[88:91]
	v_mfma_f32_16x16x32_bf16 v[76:79], v[126:129], v[202:205], v[76:79]
	v_mfma_f32_16x16x32_bf16 v[72:75], v[142:145], v[202:205], v[72:75]
	v_mfma_f32_16x16x32_bf16 v[138:141], v[130:133], v[170:173], v[138:141]
	v_mfma_f32_16x16x32_bf16 v[134:137], v[146:149], v[170:173], v[134:137]
	v_mfma_f32_16x16x32_bf16 v[114:117], v[130:133], v[178:181], v[114:117]
	v_mfma_f32_16x16x32_bf16 v[110:113], v[146:149], v[178:181], v[110:113]
	v_mfma_f32_16x16x32_bf16 v[92:95], v[130:133], v[198:201], v[92:95]
	v_mfma_f32_16x16x32_bf16 v[88:91], v[146:149], v[198:201], v[88:91]
	v_mfma_f32_16x16x32_bf16 v[76:79], v[130:133], v[206:209], v[76:79]
	v_mfma_f32_16x16x32_bf16 v[72:75], v[146:149], v[206:209], v[72:75]
	v_mfma_f32_16x16x32_bf16 v[122:125], v[150:153], v[166:169], v[122:125]
	v_mfma_f32_16x16x32_bf16 v[118:121], v[158:161], v[166:169], v[118:121]
	v_mfma_f32_16x16x32_bf16 v[106:109], v[150:153], v[174:177], v[106:109]
	v_mfma_f32_16x16x32_bf16 v[102:105], v[158:161], v[174:177], v[102:105]
	v_mfma_f32_16x16x32_bf16 v[84:87], v[150:153], v[194:197], v[84:87]
	v_mfma_f32_16x16x32_bf16 v[80:83], v[158:161], v[194:197], v[80:83]
	v_mfma_f32_16x16x32_bf16 v[68:71], v[150:153], v[202:205], v[68:71]
	v_mfma_f32_16x16x32_bf16 v[64:67], v[158:161], v[202:205], v[64:67]
	v_mfma_f32_16x16x32_bf16 v[122:125], v[154:157], v[170:173], v[122:125]
	v_mfma_f32_16x16x32_bf16 v[118:121], v[162:165], v[170:173], v[118:121]
	v_mfma_f32_16x16x32_bf16 v[106:109], v[154:157], v[178:181], v[106:109]
	v_mfma_f32_16x16x32_bf16 v[102:105], v[162:165], v[178:181], v[102:105]
	v_mfma_f32_16x16x32_bf16 v[84:87], v[154:157], v[198:201], v[84:87]
	v_mfma_f32_16x16x32_bf16 v[80:83], v[162:165], v[198:201], v[80:83]
	v_mfma_f32_16x16x32_bf16 v[68:71], v[154:157], v[206:209], v[68:71]
	v_mfma_f32_16x16x32_bf16 v[64:67], v[162:165], v[206:209], v[64:67]
	s_barrier
	s_setprio 0
	s_add_i32 s77, s77, s61
	v_lshl_add_u64 v[210:211], s[56:57], 0, v[96:97]
	s_mov_b32 m0, s77
	ds_read_b128 v[166:169], v236 offset:16384
	ds_read_b128 v[170:173], v236 offset:17408
	ds_read_b128 v[174:177], v236 offset:18432
	ds_read_b128 v[178:181], v236 offset:19456
	ds_read_b128 v[194:197], v236 offset:20480
	ds_read_b128 v[198:201], v236 offset:21504
	ds_read_b128 v[202:205], v236 offset:22528
	ds_read_b128 v[206:209], v236 offset:23552
	global_load_lds_dwordx4 v[210:211], off
	s_add_i32 m0, s77, 0x2000
	s_add_u32 s78, s56, 0x80000
	v_lshl_add_u64 v[212:213], s[56:57], 0, v[98:99]
	s_addc_u32 s79, s57, 0
	s_add_i32 s77, s80, s61
	global_load_lds_dwordx4 v[212:213], off
	v_lshl_add_u64 v[214:215], s[78:79], 0, v[96:97]
	s_mov_b32 m0, s77
	v_lshl_add_u64 v[216:217], s[58:59], 0, v[186:187]
	global_load_lds_dwordx4 v[214:215], off
	v_lshl_add_u64 v[214:215], s[78:79], 0, v[98:99]
	s_add_i32 m0, s77, 0x2000
	s_nop 0
	global_load_lds_dwordx4 v[214:215], off
	v_lshl_add_u64 v[214:215], s[58:59], 0, v[188:189]
	s_mov_b32 m0, s62
	s_nop 0
	global_load_lds_dwordx4 v[214:215], off
	s_mov_b32 m0, s63
	s_nop 0
	global_load_lds_dwordx4 v[216:217], off
	s_waitcnt vmcnt(8)
	s_waitcnt lgkmcnt(0)
	v_mfma_f32_16x16x32_bf16 v[60:63], v[126:129], v[166:169], v[60:63]
	v_mfma_f32_16x16x32_bf16 v[56:59], v[142:145], v[166:169], v[56:59]
	v_mfma_f32_16x16x32_bf16 v[44:47], v[126:129], v[174:177], v[44:47]
	v_mfma_f32_16x16x32_bf16 v[40:43], v[142:145], v[174:177], v[40:43]
	s_setprio 1
	s_barrier
; #define PG8_STAGE(bufoff, gbase, voff) do { _Pragma("unroll") for (int _i = 0; _i < 2; ++_i) \
;         __builtin_amdgcn_global_load_lds((const unsigned*)((const char*)(gbase) + (voff)[_i]), (PG8_LAS unsigned*)(lds + (bufoff) + ldsw + _i * 8192), 16, 0, 0); } while (0)
; #define PG8_LDA(dst, b, h) do { _Pragma("unroll") for (int m = 0; m < 4; ++m) _Pragma("unroll") for (int k = 0; k < 2; ++k) dst[m][k] = *(const PG8_LAS bf16x8*)(lds + PG8_SA(b, h) + aoff + m * 2048 + k * 1024); } while (0)
; #define PG8_LDB(dst, b, h) do { _Pragma("unroll") for (int n = 0; n < 2; ++n) _Pragma("unroll") for (int k = 0; k < 2; ++k) dst[n][k] = *(const PG8_LAS bf16x8*)(lds + PG8_SB(b, h) + boff + n * 2048 + k * 1024); } while (0)
; #define PG8_MMA(ai, bj, At, Bt) do { __builtin_amdgcn_s_setprio(1); _Pragma("unroll") for (int m = 0; m < 4; ++m) _Pragma("unroll") for (int n = 0; n < 2; ++n) _Pragma("unroll") for (int k = 0; k < 2; ++k) \
;         acc[ai][bj][m][n] = __builtin_amdgcn_mfma_f32_16x16x32_bf16(Bt[n][k], At[m][k], acc[ai][bj][m][n], 0, 0, 0); __builtin_amdgcn_s_setprio(0); } while (0)
; #define PG8_WAIT_V(n) asm volatile("s_waitcnt vmcnt(" #n ")" ::: "memory")
; #define PG8_WAIT_L(n) asm volatile("s_waitcnt lgkmcnt(" #n ")" ::: "memory")
; #define PG8_BAR __builtin_amdgcn_s_barrier()
; #define PG8_SCHED __builtin_amdgcn_sched_barrier(0)
; template <class Epi, class Sched, bool ALIGN_EPI = false, bool SP2 = false>
; __device__ __forceinline__ void gemm_phase(PG8_LAS unsigned char* lds, const Gemm g, const Sched& S, const Epi& E, const int tid) {
;     ...
;             PG8_WAIT_V(8); PG8_WAIT_L(0); PG8_BAR; PG8_MMA(1, 0, At, B0); PG8_MMA(1, 1, At, B1); PG8_BAR; PG8_SCHED;
;             PG8_LDB(B0, 1, 0); PG8_LDB(B1, 1, 1); PG8_SCHED; PG8_LDA(At, 1, 0); PG8_STAGE(PG8_SA(0, 1), a2 + hstep, voffA);
;             PG8_WAIT_V(8); PG8_WAIT_L(0); PG8_BAR; PG8_MMA(0, 0, At, B0); PG8_MMA(0, 1, At, B1); PG8_BAR; PG8_SCHED;
	v_mfma_f32_16x16x32_bf16 v[28:31], v[126:129], v[194:197], v[28:31]
	v_mfma_f32_16x16x32_bf16 v[24:27], v[142:145], v[194:197], v[24:27]
	v_mfma_f32_16x16x32_bf16 v[12:15], v[126:129], v[202:205], v[12:15]
	v_mfma_f32_16x16x32_bf16 v[8:11], v[142:145], v[202:205], v[8:11]
	v_mfma_f32_16x16x32_bf16 v[60:63], v[130:133], v[170:173], v[60:63]
	v_mfma_f32_16x16x32_bf16 v[56:59], v[146:149], v[170:173], v[56:59]
	v_mfma_f32_16x16x32_bf16 v[44:47], v[130:133], v[178:181], v[44:47]
	v_mfma_f32_16x16x32_bf16 v[40:43], v[146:149], v[178:181], v[40:43]
	v_mfma_f32_16x16x32_bf16 v[28:31], v[130:133], v[198:201], v[28:31]
	v_mfma_f32_16x16x32_bf16 v[24:27], v[146:149], v[198:201], v[24:27]
	v_mfma_f32_16x16x32_bf16 v[12:15], v[130:133], v[206:209], v[12:15]
	v_mfma_f32_16x16x32_bf16 v[8:11], v[146:149], v[206:209], v[8:11]
	v_mfma_f32_16x16x32_bf16 v[52:55], v[150:153], v[166:169], v[52:55]
	v_mfma_f32_16x16x32_bf16 v[48:51], v[158:161], v[166:169], v[48:51]
	v_mfma_f32_16x16x32_bf16 v[36:39], v[150:153], v[174:177], v[36:39]
	v_mfma_f32_16x16x32_bf16 v[32:35], v[158:161], v[174:177], v[32:35]
	v_mfma_f32_16x16x32_bf16 v[20:23], v[150:153], v[194:197], v[20:23]
	v_mfma_f32_16x16x32_bf16 v[16:19], v[158:161], v[194:197], v[16:19]
	v_mfma_f32_16x16x32_bf16 v[4:7], v[150:153], v[202:205], v[4:7]
	v_mfma_f32_16x16x32_bf16 v[0:3], v[158:161], v[202:205], v[0:3]
	v_mfma_f32_16x16x32_bf16 v[52:55], v[154:157], v[170:173], v[52:55]
	v_mfma_f32_16x16x32_bf16 v[48:51], v[162:165], v[170:173], v[48:51]
	v_mfma_f32_16x16x32_bf16 v[36:39], v[154:157], v[178:181], v[36:39]
	v_mfma_f32_16x16x32_bf16 v[32:35], v[162:165], v[178:181], v[32:35]
	v_mfma_f32_16x16x32_bf16 v[20:23], v[154:157], v[198:201], v[20:23]
	v_mfma_f32_16x16x32_bf16 v[16:19], v[162:165], v[198:201], v[16:19]
	v_mfma_f32_16x16x32_bf16 v[4:7], v[154:157], v[206:209], v[4:7]
	v_mfma_f32_16x16x32_bf16 v[0:3], v[162:165], v[206:209], v[0:3]
	s_barrier
	s_setprio 0
	s_add_i32 s77, 0, 0x18000
	s_add_i32 s78, 0, 0x1c000
	v_add_u32_e32 v146, s77, v233
	v_add_u32_e32 v162, s78, v233
	ds_read_b128 v[126:129], v146
	ds_read_b128 v[130:133], v146 offset:1024
	ds_read_b128 v[142:145], v146 offset:2048
	ds_read_b128 v[146:149], v146 offset:3072
	ds_read_b128 v[150:153], v162
	ds_read_b128 v[154:157], v162 offset:1024
	ds_read_b128 v[158:161], v162 offset:2048
	ds_read_b128 v[162:165], v162 offset:3072
	s_add_u32 s58, s58, 0x80000
	s_addc_u32 s59, s59, 0
	s_mov_b32 m0, s64
	v_lshl_add_u64 v[218:219], s[58:59], 0, v[188:189]
	ds_read_b128 v[166:169], v236 offset:32768
	ds_read_b128 v[170:173], v236 offset:33792
	ds_read_b128 v[174:177], v236 offset:34816
	ds_read_b128 v[178:181], v236 offset:35840
	ds_read_b128 v[194:197], v236 offset:36864
	ds_read_b128 v[198:201], v236 offset:37888
	ds_read_b128 v[202:205], v236 offset:38912
	ds_read_b128 v[206:209], v236 offset:39936
	global_load_lds_dwordx4 v[218:219], off
	v_lshl_add_u64 v[218:219], s[58:59], 0, v[186:187]
	s_mov_b32 m0, s65
	s_nop 0
	global_load_lds_dwordx4 v[218:219], off
	s_waitcnt vmcnt(8)
	s_waitcnt lgkmcnt(0)
	v_mfma_f32_16x16x32_bf16 v[138:141], v[126:129], v[166:169], v[138:141]
	v_mfma_f32_16x16x32_bf16 v[134:137], v[142:145], v[166:169], v[134:137]
	v_mfma_f32_16x16x32_bf16 v[114:117], v[126:129], v[174:177], v[114:117]
	v_mfma_f32_16x16x32_bf16 v[110:113], v[142:145], v[174:177], v[110:113]
	s_setprio 1
	s_barrier
	v_mfma_f32_16x16x32_bf16 v[92:95], v[126:129], v[194:197], v[92:95]
	v_mfma_f32_16x16x32_bf16 v[88:91], v[142:145], v[194:197], v[88:91]
	v_mfma_f32_16x16x32_bf16 v[76:79], v[126:129], v[202:205], v[76:79]
	v_mfma_f32_16x16x32_bf16 v[72:75], v[142:145], v[202:205], v[72:75]
	v_mfma_f32_16x16x32_bf16 v[138:141], v[130:133], v[170:173], v[138:141]
	v_mfma_f32_16x16x32_bf16 v[134:137], v[146:149], v[170:173], v[134:137]
	v_mfma_f32_16x16x32_bf16 v[114:117], v[130:133], v[178:181], v[114:117]
	v_mfma_f32_16x16x32_bf16 v[110:113], v[146:149], v[178:181], v[110:113]
	v_mfma_f32_16x16x32_bf16 v[92:95], v[130:133], v[198:201], v[92:95]
	v_mfma_f32_16x16x32_bf16 v[88:91], v[146:149], v[198:201], v[88:91]
	v_mfma_f32_16x16x32_bf16 v[76:79], v[130:133], v[206:209], v[76:79]
	v_mfma_f32_16x16x32_bf16 v[72:75], v[146:149], v[206:209], v[72:75]
	v_mfma_f32_16x16x32_bf16 v[122:125], v[150:153], v[166:169], v[122:125]
	v_mfma_f32_16x16x32_bf16 v[118:121], v[158:161], v[166:169], v[118:121]
	v_mfma_f32_16x16x32_bf16 v[106:109], v[150:153], v[174:177], v[106:109]
	v_mfma_f32_16x16x32_bf16 v[102:105], v[158:161], v[174:177], v[102:105]
	v_mfma_f32_16x16x32_bf16 v[84:87], v[150:153], v[194:197], v[84:87]
	v_mfma_f32_16x16x32_bf16 v[80:83], v[158:161], v[194:197], v[80:83]
	v_mfma_f32_16x16x32_bf16 v[68:71], v[150:153], v[202:205], v[68:71]
	v_mfma_f32_16x16x32_bf16 v[64:67], v[158:161], v[202:205], v[64:67]
	v_mfma_f32_16x16x32_bf16 v[122:125], v[154:157], v[170:173], v[122:125]
	v_mfma_f32_16x16x32_bf16 v[118:121], v[162:165], v[170:173], v[118:121]
	v_mfma_f32_16x16x32_bf16 v[106:109], v[154:157], v[178:181], v[106:109]
	v_mfma_f32_16x16x32_bf16 v[102:105], v[162:165], v[178:181], v[102:105]
	v_mfma_f32_16x16x32_bf16 v[84:87], v[154:157], v[198:201], v[84:87]
	v_mfma_f32_16x16x32_bf16 v[80:83], v[162:165], v[198:201], v[80:83]
	v_mfma_f32_16x16x32_bf16 v[68:71], v[154:157], v[206:209], v[68:71]
	v_mfma_f32_16x16x32_bf16 v[64:67], v[162:165], v[206:209], v[64:67]
	s_barrier
; #define PG8_GAS __attribute__((address_space(1)))
; #define PG8_STAGE(bufoff, gbase, voff) do { _Pragma("unroll") for (int _i = 0; _i < 2; ++_i) \
;         __builtin_amdgcn_global_load_lds((const unsigned*)((const char*)(gbase) + (voff)[_i]), (PG8_LAS unsigned*)(lds + (bufoff) + ldsw + _i * 8192), 16, 0, 0); } while (0)
; #define PG8_LDA(dst, b, h) do { _Pragma("unroll") for (int m = 0; m < 4; ++m) _Pragma("unroll") for (int k = 0; k < 2; ++k) dst[m][k] = *(const PG8_LAS bf16x8*)(lds + PG8_SA(b, h) + aoff + m * 2048 + k * 1024); } while (0)
; #define PG8_MMA(ai, bj, At, Bt) do { __builtin_amdgcn_s_setprio(1); _Pragma("unroll") for (int m = 0; m < 4; ++m) _Pragma("unroll") for (int n = 0; n < 2; ++n) _Pragma("unroll") for (int k = 0; k < 2; ++k) \
;         acc[ai][bj][m][n] = __builtin_amdgcn_mfma_f32_16x16x32_bf16(Bt[n][k], At[m][k], acc[ai][bj][m][n], 0, 0, 0); __builtin_amdgcn_s_setprio(0); } while (0)
; #define PG8_WAIT_V(n) asm volatile("s_waitcnt vmcnt(" #n ")" ::: "memory")
; #define PG8_WAIT_L(n) asm volatile("s_waitcnt lgkmcnt(" #n ")" ::: "memory")
; #define PG8_BAR __builtin_amdgcn_s_barrier()
;     __device__ __forceinline__ void operator()(const f32x4 (&acc)[2][2][4][2], const Unit& u, int wr, int wc, int fr, int fq) const {
;         const int row0 = u.pm * BM + wr * 64 + fr, col0 = u.pn * BM + wc * 32 + 8 * fq, lcol = u.pn * BM + (wc * 4 + fq) * 16;
; #pragma unroll
;         for (int ai = 0; ai < 2; ++ai) {
;             u32x4 L4[4], H4[4][2];
; #pragma unroll
;             for (int m = 0; m < 4; ++m) {
;                 const int row = row0 + ai * HALF + m * 16; const size_t off = (size_t)row * 2048 + col0, loff = (size_t)row * 2048 + lcol;
;                 L4[m] = *(const PG8_GAS u32x4*)(lin + loff); H4[m][0] = *(const PG8_GAS u32x4*)(hin + off); H4[m][1] = *(const PG8_GAS u32x4*)(hin + off + HALF);
;             }
; template <class Epi, class Sched, bool ALIGN_EPI = false, bool SP2 = false>
; __device__ __forceinline__ void gemm_phase(PG8_LAS unsigned char* lds, const Gemm g, const Sched& S, const Epi& E, const int tid) {
;     ...
;             PG8_LDA(At, 1, 1); PG8_STAGE(PG8_SB(1, 0), b3, voffB); PG8_STAGE(PG8_SB(1, 1), b3 + hstep, voffB); PG8_STAGE(PG8_SA(1, 0), a3, voffA);
;             PG8_WAIT_V(8); PG8_WAIT_L(0); PG8_BAR; PG8_MMA(1, 0, At, B0); PG8_MMA(1, 1, At, B1); PG8_BAR; PG8_SCHED;
	s_setprio 0
	s_add_i32 s58, s77, s61
	v_lshl_add_u64 v[210:211], v[210:211], 0, s[28:29]
	s_mov_b32 m0, s58
	ds_read_b128 v[166:169], v236 offset:49152
	ds_read_b128 v[170:173], v236 offset:50176
	ds_read_b128 v[174:177], v236 offset:51200
	ds_read_b128 v[178:181], v236 offset:52224
	ds_read_b128 v[194:197], v236 offset:53248
	ds_read_b128 v[198:201], v236 offset:54272
	ds_read_b128 v[202:205], v236 offset:55296
	ds_read_b128 v[206:209], v236 offset:56320
	global_load_lds_dwordx4 v[210:211], off
	s_add_i32 m0, s58, 0x2000
	s_add_u32 s56, s56, 0x80080
	v_lshl_add_u64 v[210:211], v[212:213], 0, s[28:29]
	s_addc_u32 s57, s57, 0
	s_add_i32 s58, s78, s61
	global_load_lds_dwordx4 v[210:211], off
	v_lshl_add_u64 v[210:211], s[56:57], 0, v[96:97]
	s_mov_b32 m0, s58
	s_nop 0
	global_load_lds_dwordx4 v[210:211], off
	v_lshl_add_u64 v[210:211], s[56:57], 0, v[98:99]
	s_add_i32 m0, s58, 0x2000
	s_nop 0
	global_load_lds_dwordx4 v[210:211], off
	v_lshl_add_u64 v[210:211], v[214:215], 0, s[28:29]
	s_mov_b32 m0, s66
	s_nop 0
	global_load_lds_dwordx4 v[210:211], off
	v_lshl_add_u64 v[210:211], v[216:217], 0, s[28:29]
	s_mov_b32 m0, s67
	s_nop 0
	global_load_lds_dwordx4 v[210:211], off
	s_waitcnt vmcnt(8)
	s_waitcnt lgkmcnt(0)
	v_mfma_f32_16x16x32_bf16 v[60:63], v[126:129], v[166:169], v[60:63]
	v_mfma_f32_16x16x32_bf16 v[56:59], v[142:145], v[166:169], v[56:59]
	v_mfma_f32_16x16x32_bf16 v[44:47], v[126:129], v[174:177], v[44:47]
	v_mfma_f32_16x16x32_bf16 v[40:43], v[142:145], v[174:177], v[40:43]
	s_setprio 1
	s_barrier
	v_mfma_f32_16x16x32_bf16 v[28:31], v[126:129], v[194:197], v[28:31]
	v_mfma_f32_16x16x32_bf16 v[24:27], v[142:145], v[194:197], v[24:27]
	v_mfma_f32_16x16x32_bf16 v[12:15], v[126:129], v[202:205], v[12:15]
	v_mfma_f32_16x16x32_bf16 v[8:11], v[142:145], v[202:205], v[8:11]
	v_mfma_f32_16x16x32_bf16 v[60:63], v[130:133], v[170:173], v[60:63]
	v_mfma_f32_16x16x32_bf16 v[56:59], v[146:149], v[170:173], v[56:59]
	v_mfma_f32_16x16x32_bf16 v[44:47], v[130:133], v[178:181], v[44:47]
	v_mfma_f32_16x16x32_bf16 v[40:43], v[146:149], v[178:181], v[40:43]
	v_mfma_f32_16x16x32_bf16 v[28:31], v[130:133], v[198:201], v[28:31]
	v_mfma_f32_16x16x32_bf16 v[24:27], v[146:149], v[198:201], v[24:27]
	v_mfma_f32_16x16x32_bf16 v[12:15], v[130:133], v[206:209], v[12:15]
	v_mfma_f32_16x16x32_bf16 v[8:11], v[146:149], v[206:209], v[8:11]
	v_mfma_f32_16x16x32_bf16 v[52:55], v[150:153], v[166:169], v[52:55]
	v_mfma_f32_16x16x32_bf16 v[48:51], v[158:161], v[166:169], v[48:51]
	v_mfma_f32_16x16x32_bf16 v[36:39], v[150:153], v[174:177], v[36:39]
	v_mfma_f32_16x16x32_bf16 v[32:35], v[158:161], v[174:177], v[32:35]
	v_mfma_f32_16x16x32_bf16 v[20:23], v[150:153], v[194:197], v[20:23]
	v_mfma_f32_16x16x32_bf16 v[16:19], v[158:161], v[194:197], v[16:19]
	v_mfma_f32_16x16x32_bf16 v[4:7], v[150:153], v[202:205], v[4:7]
	v_mfma_f32_16x16x32_bf16 v[0:3], v[158:161], v[202:205], v[0:3]
	v_mfma_f32_16x16x32_bf16 v[52:55], v[154:157], v[170:173], v[52:55]
	v_mfma_f32_16x16x32_bf16 v[48:51], v[162:165], v[170:173], v[48:51]
	v_mfma_f32_16x16x32_bf16 v[36:39], v[154:157], v[178:181], v[36:39]
	v_mfma_f32_16x16x32_bf16 v[32:35], v[162:165], v[178:181], v[32:35]
	v_mfma_f32_16x16x32_bf16 v[20:23], v[154:157], v[198:201], v[20:23]
	v_mfma_f32_16x16x32_bf16 v[16:19], v[162:165], v[198:201], v[16:19]
	v_mfma_f32_16x16x32_bf16 v[4:7], v[154:157], v[206:209], v[4:7]
	v_mfma_f32_16x16x32_bf16 v[0:3], v[162:165], v[206:209], v[0:3]
	s_barrier
	s_setprio 0
	s_add_i32 s76, s76, 2
	s_add_u32 s73, s73, 0x100
	s_addc_u32 s75, s75, 0
	s_add_u32 s54, s54, 0x100
	s_addc_u32 s55, s55, 0
	s_cmp_gt_u32 s76, 29
	s_cbranch_scc0 .LBB0_1199
	v_and_b32_e32 v127, 64, v228
	v_xor_b32_e32 v126, 16, v228
	v_add_u32_e32 v127, 64, v127
	v_cmp_lt_i32_e32 vcc, v126, v127
	s_lshl_b32 s47, s69, 8
	v_lshl_add_u32 v198, s70, 8, v101
	v_cndmask_b32_e32 v126, v228, v126, vcc
	v_or_b32_e32 v194, s47, v235
	v_lshlrev_b32_e32 v238, 2, v126
	v_xor_b32_e32 v126, 32, v228
	v_or_b32_e32 v196, s47, v234
	v_ashrrev_i32_e32 v195, 31, v194
	v_cmp_lt_i32_e32 vcc, v126, v127
	v_ashrrev_i32_e32 v199, 31, v198
	v_ashrrev_i32_e32 v197, 31, v196
	v_cndmask_b32_e32 v126, v228, v126, vcc
	v_lshl_add_u64 v[202:203], s[34:35], 0, v[194:195]
	v_lshlrev_b64 v[216:217], 11, v[198:199]
	v_lshlrev_b32_e32 v237, 2, v126
	v_lshlrev_b64 v[218:219], 1, v[196:197]
	v_lshl_add_u64 v[126:127], v[202:203], 0, v[216:217]
	v_lshl_add_u64 v[200:201], s[30:31], 0, v[218:219]
	global_load_dwordx4 v[170:173], v[126:127], off
	v_lshlrev_b64 v[220:221], 12, v[198:199]
	v_lshl_add_u64 v[126:127], v[200:201], 0, v[220:221]
	global_load_dwordx4 v[178:181], v[126:127], off
	global_load_dwordx4 v[174:177], v[126:127], off offset:256
	v_or_b32_e32 v212, 16, v198
	v_ashrrev_i32_e32 v213, 31, v212
	v_lshlrev_b64 v[214:215], 11, v[212:213]
	v_lshl_add_u64 v[126:127], v[202:203], 0, v[214:215]
	v_or_b32_e32 v208, 32, v198
	global_load_dwordx4 v[158:161], v[126:127], off
	v_lshlrev_b64 v[126:127], 12, v[212:213]
	v_ashrrev_i32_e32 v209, 31, v208
	v_lshl_add_u64 v[126:127], v[200:201], 0, v[126:127]
	v_lshlrev_b64 v[210:211], 11, v[208:209]
	global_load_dwordx4 v[166:169], v[126:127], off
	global_load_dwordx4 v[162:165], v[126:127], off offset:256
	v_lshl_add_u64 v[126:127], v[202:203], 0, v[210:211]
	v_or_b32_e32 v204, 48, v198
	global_load_dwordx4 v[146:149], v[126:127], off
	v_lshlrev_b64 v[126:127], 12, v[208:209]
	v_ashrrev_i32_e32 v205, 31, v204
	v_lshl_add_u64 v[126:127], v[200:201], 0, v[126:127]
	v_lshlrev_b64 v[206:207], 11, v[204:205]
	v_lshlrev_b64 v[130:131], 12, v[204:205]
	global_load_dwordx4 v[154:157], v[126:127], off
	global_load_dwordx4 v[150:153], v[126:127], off offset:256
	v_lshl_add_u64 v[126:127], v[202:203], 0, v[206:207]
	v_lshl_add_u64 v[130:131], v[200:201], 0, v[130:131]
	global_load_dwordx4 v[126:129], v[126:127], off
	s_nop 0
	global_load_dwordx4 v[142:145], v[130:131], off
	s_nop 0
	global_load_dwordx4 v[130:133], v[130:131], off offset:256
	v_mov_b32_e32 v225, v134
	v_mov_b32_e32 v243, v136
	v_mov_b32_e32 v242, v140
	s_waitcnt vmcnt(0)
; #define PG8_GAS __attribute__((address_space(1)))
; __device__ __forceinline__ float e_x24(unsigned h16, unsigned l8) { return __uint_as_float(((h16 - (l8 >> 7)) << 16) | (l8 << 8)); }
;     __device__ __forceinline__ void operator()(const f32x4 (&acc)[2][2][4][2], const Unit& u, int wr, int wc, int fr, int fq) const {
;     ...
;             for (int m = 0; m < 4; ++m) {
;                 const int row = row0 + ai * HALF + m * 16; const size_t off = (size_t)row * 2048 + col0, loff = (size_t)row * 2048 + lcol; float ss = 0.f;
;                 const u32x4 l4 = L4[m];
;                 u32x4 lo4;
; #pragma unroll
;                 for (int bj = 0; bj < 2; ++bj) {
;                     const u32x4 h4 = H4[m][bj];
;                     u32x4 ho;
; #pragma unroll
;                     for (int j = 0; j < 4; ++j) {
;                         const unsigned lw = l4[2 * bj + (j >> 1)], lb0 = (lw >> (16 * (j & 1))) & 0xffu, lb1 = (lw >> (16 * (j & 1) + 8)) & 0xffu;
;                         const float x0 = e_x24(h4[j] & 0xffffu, lb0) + acc[ai][bj][m][j >> 1][2 * (j & 1)] * scale, x1 = e_x24(h4[j] >> 16, lb1) + acc[ai][bj][m][j >> 1][2 * (j & 1) + 1] * scale;
;                         const unsigned b0 = __float_as_uint(x0), b1 = __float_as_uint(x1);
;                         ho[j] = ((b0 + 0x8000u) >> 16) | ((b1 + 0x8000u) & 0xffff0000u);
;                         const unsigned nb = ((b0 >> 8) & 0xffu) | (b1 & 0xff00u);
;                         if ((j & 1) == 0) lo4[2 * bj + (j >> 1)] = nb; else lo4[2 * bj + (j >> 1)] |= nb << 16;
;                         ss += x0 * x0 + x1 * x1;
;                     }
;                     *(PG8_GAS u32x4*)(hout + off + bj * HALF) = ho;
	v_lshrrev_b32_sdwa v182, v229, v171 dst_sel:DWORD dst_unused:UNUSED_PAD src0_sel:DWORD src1_sel:BYTE_0
	v_lshrrev_b32_sdwa v183, v229, v170 dst_sel:DWORD dst_unused:UNUSED_PAD src0_sel:DWORD src1_sel:BYTE_0
	v_sub_u32_sdwa v183, v178, v183 dst_sel:WORD_1 dst_unused:UNUSED_PAD src0_sel:DWORD src1_sel:DWORD
	v_sub_u32_sdwa v182, v180, v182 dst_sel:WORD_1 dst_unused:UNUSED_PAD src0_sel:DWORD src1_sel:DWORD
	v_lshlrev_b32_sdwa v222, v230, v171 dst_sel:DWORD dst_unused:UNUSED_PAD src0_sel:DWORD src1_sel:BYTE_0
	v_lshlrev_b32_sdwa v224, v230, v170 dst_sel:DWORD dst_unused:UNUSED_PAD src0_sel:DWORD src1_sel:BYTE_0
	v_or_b32_e32 v223, v182, v222
	v_or_b32_e32 v222, v183, v224
	v_mov_b32_e32 v224, v138
	v_pk_add_f32 v[222:223], v[224:225], v[222:223]
	v_lshlrev_b32_e32 v182, 1, v170
	v_add_u32_e32 v134, 0x8000, v222
	v_lshrrev_b32_e32 v138, 16, v134
	v_lshlrev_b32_e32 v134, 1, v171
	v_and_b32_e32 v134, 0x10000, v134
	v_and_b32_e32 v182, 0x10000, v182
	v_sub_u32_e32 v134, v180, v134
	v_sub_u32_e32 v178, v178, v182
	v_and_b32_e32 v134, 0xffff0000, v134
	v_and_b32_e32 v178, 0xffff0000, v178
	v_and_b32_e32 v180, 0xff00, v171
	v_and_b32_e32 v182, 0xff00, v170
	v_or_b32_e32 v225, v134, v180
	v_or_b32_e32 v224, v178, v182
	v_mov_b32_e32 v134, v139
	v_pk_add_f32 v[224:225], v[134:135], v[224:225]
	v_and_b32_sdwa v135, v171, s93 dst_sel:DWORD dst_unused:UNUSED_PAD src0_sel:WORD_1 src1_sel:DWORD
	v_and_b32_sdwa v178, v170, s93 dst_sel:DWORD dst_unused:UNUSED_PAD src0_sel:WORD_1 src1_sel:DWORD
	v_lshlrev_b32_sdwa v182, v231, v170 dst_sel:DWORD dst_unused:UNUSED_PAD src0_sel:DWORD src1_sel:BYTE_3
	v_lshlrev_b32_sdwa v136, v231, v171 dst_sel:DWORD dst_unused:UNUSED_PAD src0_sel:DWORD src1_sel:BYTE_3
	v_lshrrev_b32_e32 v180, 7, v178
	v_lshrrev_b32_e32 v183, 7, v135
	v_and_b32_e32 v136, 0x10000, v136
	v_and_b32_e32 v140, 0x10000, v182
	v_sub_u32_sdwa v180, v179, v180 dst_sel:WORD_1 dst_unused:UNUSED_PAD src0_sel:DWORD src1_sel:DWORD
	v_sub_u32_sdwa v183, v181, v183 dst_sel:WORD_1 dst_unused:UNUSED_PAD src0_sel:DWORD src1_sel:DWORD
	v_lshlrev_b32_e32 v135, 8, v135
	v_lshlrev_b32_e32 v178, 8, v178
	v_sub_u32_e32 v136, v181, v136
	v_sub_u32_e32 v140, v179, v140
	v_or_b32_e32 v241, v183, v135
	v_or_b32_e32 v240, v180, v178
	v_and_b32_e32 v136, 0xffff0000, v136
	v_and_b32_e32 v140, 0xffff0000, v140
	v_lshlrev_b32_sdwa v171, v230, v171 dst_sel:DWORD dst_unused:UNUSED_PAD src0_sel:DWORD src1_sel:BYTE_3
	v_lshlrev_b32_sdwa v170, v230, v170 dst_sel:DWORD dst_unused:UNUSED_PAD src0_sel:DWORD src1_sel:BYTE_3
	v_pk_add_f32 v[240:241], v[242:243], v[240:241]
	v_or_b32_e32 v171, v136, v171
	v_or_b32_e32 v170, v140, v170
	v_mov_b32_e32 v136, v141
	v_add_u32_e32 v135, 0x8000, v240
	v_pk_add_f32 v[140:141], v[136:137], v[170:171]
	v_lshrrev_b32_e32 v135, 16, v135
	v_add_u32_e32 v136, 0x8000, v140
	v_and_or_b32 v135, v136, s90, v135
	v_pk_mul_f32 v[136:137], v[140:141], v[140:141]
	v_add_u32_e32 v178, 0x8000, v141
	v_pk_fma_f32 v[170:171], v[240:241], v[240:241], v[136:137]
	v_add_u32_e32 v136, 0x8000, v223
	v_lshrrev_b32_e32 v136, 16, v136
	v_add_u32_e32 v137, 0x8000, v225
	v_and_or_b32 v136, v137, s90, v136
	v_add_u32_e32 v137, 0x8000, v241
	v_lshrrev_b32_e32 v137, 16, v137
	v_add_u32_e32 v134, 0x8000, v224
	v_and_or_b32 v137, v178, s90, v137
	v_lshl_add_u64 v[178:179], s[30:31], 0, v[220:221]
	v_and_or_b32 v134, v134, s90, v138
	v_lshl_add_u64 v[178:179], v[178:179], 0, v[218:219]
	global_store_dwordx4 v[178:179], v[134:137], off
	v_lshlrev_b32_sdwa v182, v231, v172 dst_sel:DWORD dst_unused:UNUSED_PAD src0_sel:DWORD src1_sel:BYTE_3
	v_mov_b32_e32 v219, v120
	v_lshrrev_b32_sdwa v134, v229, v173 dst_sel:DWORD dst_unused:UNUSED_PAD src0_sel:DWORD src1_sel:BYTE_0
	v_lshrrev_b32_sdwa v135, v229, v172 dst_sel:DWORD dst_unused:UNUSED_PAD src0_sel:DWORD src1_sel:BYTE_0
	v_sub_u32_sdwa v136, v174, v135 dst_sel:WORD_1 dst_unused:UNUSED_PAD src0_sel:DWORD src1_sel:DWORD
	v_sub_u32_sdwa v134, v176, v134 dst_sel:WORD_1 dst_unused:UNUSED_PAD src0_sel:DWORD src1_sel:DWORD
	v_lshlrev_b32_sdwa v135, v230, v173 dst_sel:DWORD dst_unused:UNUSED_PAD src0_sel:DWORD src1_sel:BYTE_0
	v_lshlrev_b32_sdwa v137, v230, v172 dst_sel:DWORD dst_unused:UNUSED_PAD src0_sel:DWORD src1_sel:BYTE_0
	v_or_b32_e32 v135, v134, v135
	v_or_b32_e32 v134, v136, v137
	v_mov_b32_e32 v136, v122
	v_mov_b32_e32 v137, v118
	v_pk_add_f32 v[134:135], v[136:137], v[134:135]
	v_lshlrev_b32_e32 v122, 1, v172
; #define PG8_GAS __attribute__((address_space(1)))
; __device__ __forceinline__ float e_x24(unsigned h16, unsigned l8) { return __uint_as_float(((h16 - (l8 >> 7)) << 16) | (l8 << 8)); }
;     __device__ __forceinline__ void operator()(const f32x4 (&acc)[2][2][4][2], const Unit& u, int wr, int wc, int fr, int fq) const {
;     ...
;                 for (int bj = 0; bj < 2; ++bj) {
;                     const u32x4 h4 = H4[m][bj];
;                     u32x4 ho;
; #pragma unroll
;                     for (int j = 0; j < 4; ++j) {
;                         const unsigned lw = l4[2 * bj + (j >> 1)], lb0 = (lw >> (16 * (j & 1))) & 0xffu, lb1 = (lw >> (16 * (j & 1) + 8)) & 0xffu;
;                         const float x0 = e_x24(h4[j] & 0xffffu, lb0) + acc[ai][bj][m][j >> 1][2 * (j & 1)] * scale, x1 = e_x24(h4[j] >> 16, lb1) + acc[ai][bj][m][j >> 1][2 * (j & 1) + 1] * scale;
;                         const unsigned b0 = __float_as_uint(x0), b1 = __float_as_uint(x1);
;                         ho[j] = ((b0 + 0x8000u) >> 16) | ((b1 + 0x8000u) & 0xffff0000u);
;                         const unsigned nb = ((b0 >> 8) & 0xffu) | (b1 & 0xff00u);
;                         if ((j & 1) == 0) lo4[2 * bj + (j >> 1)] = nb; else lo4[2 * bj + (j >> 1)] |= nb << 16;
;                         ss += x0 * x0 + x1 * x1;
;                     }
;                     *(PG8_GAS u32x4*)(hout + off + bj * HALF) = ho;
;                 }
;                 *(PG8_GAS u32x4*)(lout + loff) = lo4;
;                 ss += __shfl_xor(ss, 16); ss += __shfl_xor(ss, 32);
;                 if (fq == 0) __hip_atomic_fetch_add((PG8_GAS unsigned long long*)(rowsq_out + row), (unsigned long long)(ss * 16777216.0f + 0.5f), __ATOMIC_RELAXED, __HIP_MEMORY_SCOPE_AGENT);
	v_add_u32_e32 v118, 0x8000, v134
	v_lshrrev_b32_e32 v180, 16, v118
	v_lshlrev_b32_e32 v118, 1, v173
	v_and_b32_e32 v118, 0x10000, v118
	v_and_b32_e32 v122, 0x10000, v122
	v_sub_u32_e32 v118, v176, v118
	v_sub_u32_e32 v122, v174, v122
	v_and_b32_e32 v118, 0xffff0000, v118
	v_and_b32_e32 v122, 0xffff0000, v122
	v_and_b32_e32 v136, 0xff00, v173
	v_and_b32_e32 v174, 0xff00, v172
	v_or_b32_e32 v137, v118, v136
	v_or_b32_e32 v136, v122, v174
	v_mov_b32_e32 v118, v123
	v_pk_add_f32 v[122:123], v[118:119], v[136:137]
	v_and_b32_sdwa v119, v173, s93 dst_sel:DWORD dst_unused:UNUSED_PAD src0_sel:WORD_1 src1_sel:DWORD
	v_add_u32_e32 v118, 0x8000, v122
	v_and_b32_sdwa v174, v172, s93 dst_sel:DWORD dst_unused:UNUSED_PAD src0_sel:WORD_1 src1_sel:DWORD
	v_lshlrev_b32_sdwa v120, v231, v173 dst_sel:DWORD dst_unused:UNUSED_PAD src0_sel:DWORD src1_sel:BYTE_3
	v_and_or_b32 v118, v118, s90, v180
	v_lshrrev_b32_e32 v176, 7, v174
	v_lshrrev_b32_e32 v180, 7, v119
	v_mov_b32_e32 v218, v124
	v_and_b32_e32 v120, 0x10000, v120
	v_and_b32_e32 v124, 0x10000, v182
	v_sub_u32_sdwa v176, v175, v176 dst_sel:WORD_1 dst_unused:UNUSED_PAD src0_sel:DWORD src1_sel:DWORD
	v_sub_u32_sdwa v180, v177, v180 dst_sel:WORD_1 dst_unused:UNUSED_PAD src0_sel:DWORD src1_sel:DWORD
	v_lshlrev_b32_e32 v119, 8, v119
	v_lshlrev_b32_e32 v174, 8, v174
	v_sub_u32_e32 v120, v177, v120
	v_sub_u32_e32 v124, v175, v124
	v_or_b32_e32 v181, v180, v119
	v_or_b32_e32 v180, v176, v174
	v_and_b32_e32 v120, 0xffff0000, v120
	v_and_b32_e32 v124, 0xffff0000, v124
	v_lshlrev_b32_sdwa v173, v230, v173 dst_sel:DWORD dst_unused:UNUSED_PAD src0_sel:DWORD src1_sel:BYTE_3
	v_lshlrev_b32_sdwa v172, v230, v172 dst_sel:DWORD dst_unused:UNUSED_PAD src0_sel:DWORD src1_sel:BYTE_3
	v_pk_add_f32 v[180:181], v[218:219], v[180:181]
	v_or_b32_e32 v173, v120, v173
	v_or_b32_e32 v172, v124, v172
	v_mov_b32_e32 v120, v125
	v_add_u32_e32 v119, 0x8000, v180
	v_pk_add_f32 v[124:125], v[120:121], v[172:173]
	v_lshrrev_b32_e32 v119, 16, v119
	v_add_u32_e32 v120, 0x8000, v124
	v_pk_mul_f32 v[138:139], v[224:225], v[224:225]
	v_pk_mul_f32 v[136:137], v[122:123], v[122:123]
	v_and_or_b32 v119, v120, s90, v119
	v_pk_mul_f32 v[120:121], v[124:125], v[124:125]
	v_pk_fma_f32 v[138:139], v[222:223], v[222:223], v[138:139]
	v_pk_fma_f32 v[136:137], v[134:135], v[134:135], v[136:137]
	v_pk_fma_f32 v[172:173], v[180:181], v[180:181], v[120:121]
	v_add_u32_e32 v120, 0x8000, v135
	v_lshrrev_b32_e32 v134, 8, v134
	v_lshrrev_b32_e32 v120, 16, v120
	v_add_u32_e32 v121, 0x8000, v123
	v_perm_b32 v122, v122, v134, s94
	v_add_f32_e32 v134, v138, v170
	v_and_or_b32 v120, v121, s90, v120
	v_add_u32_e32 v121, 0x8000, v181
	v_add_f32_e32 v134, v139, v134
	v_lshrrev_b32_e32 v121, 16, v121
	v_add_u32_e32 v174, 0x8000, v125
	v_add_f32_e32 v134, v171, v134
	v_and_or_b32 v121, v174, s90, v121
	v_lshrrev_b32_e32 v174, 8, v181
	v_lshrrev_b32_e32 v175, 8, v180
	v_add_f32_e32 v134, v136, v134
	v_lshrrev_b32_e32 v176, 8, v241
	v_lshrrev_b32_e32 v177, 8, v240
	v_perm_b32 v124, v124, v175, s94
	v_perm_b32 v125, v125, v174, s94
	v_lshrrev_b32_e32 v135, 8, v135
	v_lshrrev_b32_e32 v174, 8, v223
	v_lshrrev_b32_e32 v175, 8, v222
	v_add_f32_e32 v134, v172, v134
	v_perm_b32 v140, v140, v177, s94
	v_perm_b32 v141, v141, v176, s94
	v_perm_b32 v175, v224, v175, s94
	v_perm_b32 v174, v225, v174, s94
	v_perm_b32 v123, v123, v135, s94
	v_add_f32_e32 v134, v137, v134
	global_store_dwordx4 v[178:179], v[118:121], off offset:256
	v_lshl_or_b32 v125, v125, 16, v123
	v_lshl_or_b32 v124, v124, 16, v122
	v_lshl_add_u64 v[118:119], s[34:35], 0, v[216:217]
	v_lshl_or_b32 v123, v141, 16, v174
	v_lshl_or_b32 v122, v140, 16, v175
	v_add_f32_e32 v134, v173, v134
	v_lshl_add_u64 v[118:119], v[118:119], 0, v[194:195]
	global_store_dwordx4 v[118:119], v[122:125], off
	ds_bpermute_b32 v118, v238, v134
	s_waitcnt lgkmcnt(0)
	v_add_f32_e32 v118, v134, v118
	ds_bpermute_b32 v119, v237, v118
	s_and_saveexec_b64 s[54:55], s[40:41]
	s_mov_b32 s80, 0x4b800000
	s_cbranch_execz .LBB0_1202
	s_waitcnt lgkmcnt(0)
	v_add_f32_e32 v118, v118, v119
	v_fma_f32 v118, v118, s80, 0.5
	v_trunc_f32_e32 v118, v118
	v_mul_f32_e32 v119, 0x2f800000, v118
	v_floor_f32_e32 v119, v119
	v_fmac_f32_e32 v118, 0xcf800000, v119
	v_cvt_u32_f32_e32 v118, v118
	v_cvt_u32_f32_e32 v119, v119
	v_lshl_add_u64 v[120:121], v[198:199], 3, s[44:45]
	global_atomic_add_x2 v[120:121], v[118:119], off
